# hand-written up-GEMM conv epilogue: DPP-fused conv taps (row_shl/shr 15 for the edge lanes), packed-f32 centre tap and silu arithmetic, saddr loads/stores, exec-masked edge-row exchange
# speedup vs baseline: 1.0967x; 1.0045x over previous
.LBB0_51:
	v_mbcnt_lo_u32_b32 v212, -1, 0
	v_mbcnt_hi_u32_b32 v212, -1, v212
	s_cmp_lt_i32 s6, 16
	s_cselect_b64 vcc, -1, 0
	v_readlane_b32 s4, v238, 0
	v_readlane_b32 s5, v238, 1
	v_lshrrev_b32_e32 v213, 4, v212
	v_and_b32_e32 v212, 15, v212
	s_and_b64 s[52:53], s[88:89], vcc
	s_andn2_b64 s[68:69], vcc, s[88:89]
	v_readlane_b32 s7, v239, 62
	s_lshl_b32 s56, s3, 7
	s_or_b32 s56, s56, s7
	v_lshl_add_u32 v214, v213, 3, s56
	v_lshlrev_b32_e32 v227, 2, v214
	v_add_u32_e32 v236, 0x2c00, v227
	global_load_dwordx4 v[128:131], v227, s[76:77]
	global_load_dwordx4 v[144:147], v236, s[76:77]
	global_load_dwordx4 v[132:135], v227, s[80:81]
	global_load_dwordx4 v[148:151], v236, s[80:81]
	global_load_dwordx4 v[136:139], v227, s[86:87]
	global_load_dwordx4 v[152:155], v236, s[86:87]
	global_load_dwordx4 v[140:143], v227, s[4:5]
	global_load_dwordx4 v[156:159], v236, s[4:5]
	v_readlane_b32 s7, v239, 60
	s_lshl_b32 s3, s6, 8
	s_add_i32 s3, s3, s7
	v_add_u32_e32 v215, s3, v212
	s_movk_i32 s3, 0x1600
	v_mul_u32_u24_e32 v237, s3, v215
	v_lshl_add_u32 v237, v214, 1, v237
	v_lshlrev_b32_e32 v215, 4, v213
	v_readlane_b32 s7, v238, 9
	s_add_i32 s7, s7, 0xffffff00
	v_add_u32_e32 v226, s7, v215
	v_mov_b32_e32 v220, 0xbfb8aa3b
	v_mov_b32_e32 v221, 0xbfb8aa3b
	v_mov_b32_e32 v222, 1.0
	v_mov_b32_e32 v223, 1.0
	s_cmp_gt_i32 s6, 15
	s_cbranch_scc1 .LUPE_noex
	v_readlane_b32 s7, v238, 5
	s_nop 1
	v_add_u32_e32 v214, s7, v215
	v_cmp_eq_u32_e64 s[6:7], 0, v212
	s_mov_b64 s[8:9], exec
	s_nop 0
	s_and_b64 exec, s[8:9], s[6:7]
	ds_write_b128 v214, v[124:127]
	ds_write_b128 v214, v[60:63] offset:64
	ds_write_b128 v214, v[120:123] offset:128
	ds_write_b128 v214, v[56:59] offset:192
	ds_write_b128 v214, v[92:95] offset:512
	ds_write_b128 v214, v[28:31] offset:576
	ds_write_b128 v214, v[88:91] offset:640
	ds_write_b128 v214, v[24:27] offset:704
	s_mov_b64 exec, s[8:9]
	v_cmp_eq_u32_e64 s[6:7], 15, v212
	s_nop 1
	s_and_b64 exec, s[8:9], s[6:7]
	ds_write_b128 v214, v[100:103] offset:256
	ds_write_b128 v214, v[36:39] offset:320
	ds_write_b128 v214, v[96:99] offset:384
	ds_write_b128 v214, v[32:35] offset:448
	ds_write_b128 v214, v[72:75] offset:768
	ds_write_b128 v214, v[4:7] offset:832
	ds_write_b128 v214, v[64:67] offset:896
	ds_write_b128 v214, v[0:3] offset:960
	s_mov_b64 exec, s[8:9]
	s_waitcnt lgkmcnt(0)
	s_barrier
.LUPE_noex:
	ds_read_b128 v[172:175], v226
	ds_read_b128 v[176:179], v226 offset:128
	ds_read_b128 v[180:183], v226 offset:256
	ds_read_b128 v[184:187], v226 offset:384
	s_waitcnt vmcnt(0) lgkmcnt(0)
	v_cndmask_b32_e64 v172, 0, v172, s[52:53]
	v_cndmask_b32_e64 v173, 0, v173, s[52:53]
	v_cndmask_b32_e64 v174, 0, v174, s[52:53]
	v_cndmask_b32_e64 v175, 0, v175, s[52:53]
	v_cndmask_b32_e64 v176, 0, v176, s[52:53]
	v_cndmask_b32_e64 v177, 0, v177, s[52:53]
	v_cndmask_b32_e64 v178, 0, v178, s[52:53]
	v_cndmask_b32_e64 v179, 0, v179, s[52:53]
	v_cndmask_b32_e32 v180, 0, v180, vcc
	v_cndmask_b32_e32 v181, 0, v181, vcc
	v_cndmask_b32_e32 v182, 0, v182, vcc
	v_cndmask_b32_e32 v183, 0, v183, vcc
	v_cndmask_b32_e32 v184, 0, v184, vcc
	v_cndmask_b32_e32 v185, 0, v185, vcc
	v_cndmask_b32_e32 v186, 0, v186, vcc
	v_cndmask_b32_e32 v187, 0, v187, vcc
	v_pk_mov_b32 v[228:229], v[140:141], v[140:141] op_sel:[0,1]
	v_pk_mov_b32 v[230:231], v[142:143], v[142:143] op_sel:[0,1]
	v_pk_mov_b32 v[232:233], v[156:157], v[156:157] op_sel:[0,1]
	v_pk_mov_b32 v[234:235], v[158:159], v[158:159] op_sel:[0,1]
	v_fmac_f32_dpp v228, v124, v136 row_shl:1 row_mask:0xf bank_mask:0xf bound_ctrl:0
	v_fmac_f32_dpp v229, v125, v137 row_shl:1 row_mask:0xf bank_mask:0xf bound_ctrl:0
	v_fmac_f32_dpp v230, v126, v138 row_shl:1 row_mask:0xf bank_mask:0xf bound_ctrl:0
	v_fmac_f32_dpp v231, v127, v139 row_shl:1 row_mask:0xf bank_mask:0xf bound_ctrl:0
	v_fmac_f32_dpp v232, v120, v152 row_shl:1 row_mask:0xf bank_mask:0xf bound_ctrl:0
	v_fmac_f32_dpp v233, v121, v153 row_shl:1 row_mask:0xf bank_mask:0xf bound_ctrl:0
	v_fmac_f32_dpp v234, v122, v154 row_shl:1 row_mask:0xf bank_mask:0xf bound_ctrl:0
	v_fmac_f32_dpp v235, v123, v155 row_shl:1 row_mask:0xf bank_mask:0xf bound_ctrl:0
	v_fmac_f32_dpp v228, v116, v136 row_shr:15 row_mask:0xf bank_mask:0xf bound_ctrl:0
	v_fmac_f32_dpp v229, v117, v137 row_shr:15 row_mask:0xf bank_mask:0xf bound_ctrl:0
	v_fmac_f32_dpp v230, v118, v138 row_shr:15 row_mask:0xf bank_mask:0xf bound_ctrl:0
	v_fmac_f32_dpp v231, v119, v139 row_shr:15 row_mask:0xf bank_mask:0xf bound_ctrl:0
	v_fmac_f32_dpp v232, v112, v152 row_shr:15 row_mask:0xf bank_mask:0xf bound_ctrl:0
	v_fmac_f32_dpp v233, v113, v153 row_shr:15 row_mask:0xf bank_mask:0xf bound_ctrl:0
	v_fmac_f32_dpp v234, v114, v154 row_shr:15 row_mask:0xf bank_mask:0xf bound_ctrl:0
	v_fmac_f32_dpp v235, v115, v155 row_shr:15 row_mask:0xf bank_mask:0xf bound_ctrl:0
	v_pk_fma_f32 v[228:229], v[132:133], v[124:125], v[228:229]
	v_pk_fma_f32 v[230:231], v[134:135], v[126:127], v[230:231]
	v_pk_fma_f32 v[232:233], v[148:149], v[120:121], v[232:233]
	v_pk_fma_f32 v[234:235], v[150:151], v[122:123], v[234:235]
	v_fmac_f32_dpp v228, v124, v128 row_shr:1 row_mask:0xf bank_mask:0xf bound_ctrl:0
	v_fmac_f32_dpp v229, v125, v129 row_shr:1 row_mask:0xf bank_mask:0xf bound_ctrl:0
	v_fmac_f32_dpp v230, v126, v130 row_shr:1 row_mask:0xf bank_mask:0xf bound_ctrl:0
	v_fmac_f32_dpp v231, v127, v131 row_shr:1 row_mask:0xf bank_mask:0xf bound_ctrl:0
	v_fmac_f32_dpp v232, v120, v144 row_shr:1 row_mask:0xf bank_mask:0xf bound_ctrl:0
	v_fmac_f32_dpp v233, v121, v145 row_shr:1 row_mask:0xf bank_mask:0xf bound_ctrl:0
	v_fmac_f32_dpp v234, v122, v146 row_shr:1 row_mask:0xf bank_mask:0xf bound_ctrl:0
	v_fmac_f32_dpp v235, v123, v147 row_shr:1 row_mask:0xf bank_mask:0xf bound_ctrl:0
	v_fmac_f32_dpp v228, v172, v128 row_shl:15 row_mask:0xf bank_mask:0xf bound_ctrl:0
	v_fmac_f32_dpp v229, v173, v129 row_shl:15 row_mask:0xf bank_mask:0xf bound_ctrl:0
	v_fmac_f32_dpp v230, v174, v130 row_shl:15 row_mask:0xf bank_mask:0xf bound_ctrl:0
	v_fmac_f32_dpp v231, v175, v131 row_shl:15 row_mask:0xf bank_mask:0xf bound_ctrl:0
	v_fmac_f32_dpp v232, v176, v144 row_shl:15 row_mask:0xf bank_mask:0xf bound_ctrl:0
	v_fmac_f32_dpp v233, v177, v145 row_shl:15 row_mask:0xf bank_mask:0xf bound_ctrl:0
	v_fmac_f32_dpp v234, v178, v146 row_shl:15 row_mask:0xf bank_mask:0xf bound_ctrl:0
	v_fmac_f32_dpp v235, v179, v147 row_shl:15 row_mask:0xf bank_mask:0xf bound_ctrl:0
	v_pk_mul_f32 v[216:217], v[228:229], v[220:221]
	v_pk_mul_f32 v[218:219], v[230:231], v[220:221]
	v_exp_f32_e32 v216, v216
	v_exp_f32_e32 v217, v217
	v_exp_f32_e32 v218, v218
	v_exp_f32_e32 v219, v219
	v_pk_add_f32 v[216:217], v[216:217], v[222:223]
	v_pk_add_f32 v[218:219], v[218:219], v[222:223]
	v_rcp_f32_e32 v216, v216
	v_rcp_f32_e32 v217, v217
	v_rcp_f32_e32 v218, v218
	v_rcp_f32_e32 v219, v219
	v_pk_mul_f32 v[228:229], v[228:229], v[216:217]
	v_pk_mul_f32 v[230:231], v[230:231], v[218:219]
	v_pk_mul_f32 v[228:229], v[232:233], v[228:229]
	v_pk_mul_f32 v[230:231], v[234:235], v[230:231]
	s_mov_b64 s[8:9], s[90:91]
	v_cvt_pk_bf16_f32 v224, v228, v229
	v_cvt_pk_bf16_f32 v225, v230, v231
	global_store_dwordx2 v237, v[224:225], s[8:9]
	ds_read_b128 v[172:175], v226 offset:512
	ds_read_b128 v[176:179], v226 offset:640
	v_pk_mov_b32 v[228:229], v[140:141], v[140:141] op_sel:[0,1]
	v_pk_mov_b32 v[230:231], v[142:143], v[142:143] op_sel:[0,1]
	v_pk_mov_b32 v[232:233], v[156:157], v[156:157] op_sel:[0,1]
	v_pk_mov_b32 v[234:235], v[158:159], v[158:159] op_sel:[0,1]
	v_fmac_f32_dpp v228, v116, v136 row_shl:1 row_mask:0xf bank_mask:0xf bound_ctrl:0
	v_fmac_f32_dpp v229, v117, v137 row_shl:1 row_mask:0xf bank_mask:0xf bound_ctrl:0
	v_fmac_f32_dpp v230, v118, v138 row_shl:1 row_mask:0xf bank_mask:0xf bound_ctrl:0
	v_fmac_f32_dpp v231, v119, v139 row_shl:1 row_mask:0xf bank_mask:0xf bound_ctrl:0
	v_fmac_f32_dpp v232, v112, v152 row_shl:1 row_mask:0xf bank_mask:0xf bound_ctrl:0
	v_fmac_f32_dpp v233, v113, v153 row_shl:1 row_mask:0xf bank_mask:0xf bound_ctrl:0
	v_fmac_f32_dpp v234, v114, v154 row_shl:1 row_mask:0xf bank_mask:0xf bound_ctrl:0
	v_fmac_f32_dpp v235, v115, v155 row_shl:1 row_mask:0xf bank_mask:0xf bound_ctrl:0
	v_fmac_f32_dpp v228, v108, v136 row_shr:15 row_mask:0xf bank_mask:0xf bound_ctrl:0
	v_fmac_f32_dpp v229, v109, v137 row_shr:15 row_mask:0xf bank_mask:0xf bound_ctrl:0
	v_fmac_f32_dpp v230, v110, v138 row_shr:15 row_mask:0xf bank_mask:0xf bound_ctrl:0
	v_fmac_f32_dpp v231, v111, v139 row_shr:15 row_mask:0xf bank_mask:0xf bound_ctrl:0
	v_fmac_f32_dpp v232, v104, v152 row_shr:15 row_mask:0xf bank_mask:0xf bound_ctrl:0
	v_fmac_f32_dpp v233, v105, v153 row_shr:15 row_mask:0xf bank_mask:0xf bound_ctrl:0
	v_fmac_f32_dpp v234, v106, v154 row_shr:15 row_mask:0xf bank_mask:0xf bound_ctrl:0
	v_fmac_f32_dpp v235, v107, v155 row_shr:15 row_mask:0xf bank_mask:0xf bound_ctrl:0
	v_pk_fma_f32 v[228:229], v[132:133], v[116:117], v[228:229]
	v_pk_fma_f32 v[230:231], v[134:135], v[118:119], v[230:231]
	v_pk_fma_f32 v[232:233], v[148:149], v[112:113], v[232:233]
	v_pk_fma_f32 v[234:235], v[150:151], v[114:115], v[234:235]
	v_fmac_f32_dpp v228, v116, v128 row_shr:1 row_mask:0xf bank_mask:0xf bound_ctrl:0
	v_fmac_f32_dpp v229, v117, v129 row_shr:1 row_mask:0xf bank_mask:0xf bound_ctrl:0
	v_fmac_f32_dpp v230, v118, v130 row_shr:1 row_mask:0xf bank_mask:0xf bound_ctrl:0
	v_fmac_f32_dpp v231, v119, v131 row_shr:1 row_mask:0xf bank_mask:0xf bound_ctrl:0
	v_fmac_f32_dpp v232, v112, v144 row_shr:1 row_mask:0xf bank_mask:0xf bound_ctrl:0
	v_fmac_f32_dpp v233, v113, v145 row_shr:1 row_mask:0xf bank_mask:0xf bound_ctrl:0
	v_fmac_f32_dpp v234, v114, v146 row_shr:1 row_mask:0xf bank_mask:0xf bound_ctrl:0
	v_fmac_f32_dpp v235, v115, v147 row_shr:1 row_mask:0xf bank_mask:0xf bound_ctrl:0
	v_fmac_f32_dpp v228, v124, v128 row_shl:15 row_mask:0xf bank_mask:0xf bound_ctrl:0
	v_fmac_f32_dpp v229, v125, v129 row_shl:15 row_mask:0xf bank_mask:0xf bound_ctrl:0
	v_fmac_f32_dpp v230, v126, v130 row_shl:15 row_mask:0xf bank_mask:0xf bound_ctrl:0
	v_fmac_f32_dpp v231, v127, v131 row_shl:15 row_mask:0xf bank_mask:0xf bound_ctrl:0
	v_fmac_f32_dpp v232, v120, v144 row_shl:15 row_mask:0xf bank_mask:0xf bound_ctrl:0
	v_fmac_f32_dpp v233, v121, v145 row_shl:15 row_mask:0xf bank_mask:0xf bound_ctrl:0
	v_fmac_f32_dpp v234, v122, v146 row_shl:15 row_mask:0xf bank_mask:0xf bound_ctrl:0
	v_fmac_f32_dpp v235, v123, v147 row_shl:15 row_mask:0xf bank_mask:0xf bound_ctrl:0
	v_pk_mul_f32 v[216:217], v[228:229], v[220:221]
	v_pk_mul_f32 v[218:219], v[230:231], v[220:221]
	v_exp_f32_e32 v216, v216
	v_exp_f32_e32 v217, v217
	v_exp_f32_e32 v218, v218
	v_exp_f32_e32 v219, v219
	v_pk_add_f32 v[216:217], v[216:217], v[222:223]
	v_pk_add_f32 v[218:219], v[218:219], v[222:223]
	v_rcp_f32_e32 v216, v216
	v_rcp_f32_e32 v217, v217
	v_rcp_f32_e32 v218, v218
	v_rcp_f32_e32 v219, v219
	v_pk_mul_f32 v[228:229], v[228:229], v[216:217]
	v_pk_mul_f32 v[230:231], v[230:231], v[218:219]
	v_pk_mul_f32 v[228:229], v[232:233], v[228:229]
	v_pk_mul_f32 v[230:231], v[234:235], v[230:231]
	s_add_u32 s8, s90, 0x16000
	s_addc_u32 s9, s91, 0
	v_cvt_pk_bf16_f32 v224, v228, v229
	v_cvt_pk_bf16_f32 v225, v230, v231
	global_store_dwordx2 v237, v[224:225], s[8:9]
	v_pk_mov_b32 v[228:229], v[140:141], v[140:141] op_sel:[0,1]
	v_pk_mov_b32 v[230:231], v[142:143], v[142:143] op_sel:[0,1]
	v_pk_mov_b32 v[232:233], v[156:157], v[156:157] op_sel:[0,1]
	v_pk_mov_b32 v[234:235], v[158:159], v[158:159] op_sel:[0,1]
	v_fmac_f32_dpp v228, v108, v136 row_shl:1 row_mask:0xf bank_mask:0xf bound_ctrl:0
	v_fmac_f32_dpp v229, v109, v137 row_shl:1 row_mask:0xf bank_mask:0xf bound_ctrl:0
	v_fmac_f32_dpp v230, v110, v138 row_shl:1 row_mask:0xf bank_mask:0xf bound_ctrl:0
	v_fmac_f32_dpp v231, v111, v139 row_shl:1 row_mask:0xf bank_mask:0xf bound_ctrl:0
	v_fmac_f32_dpp v232, v104, v152 row_shl:1 row_mask:0xf bank_mask:0xf bound_ctrl:0
	v_fmac_f32_dpp v233, v105, v153 row_shl:1 row_mask:0xf bank_mask:0xf bound_ctrl:0
	v_fmac_f32_dpp v234, v106, v154 row_shl:1 row_mask:0xf bank_mask:0xf bound_ctrl:0
	v_fmac_f32_dpp v235, v107, v155 row_shl:1 row_mask:0xf bank_mask:0xf bound_ctrl:0
	v_fmac_f32_dpp v228, v100, v136 row_shr:15 row_mask:0xf bank_mask:0xf bound_ctrl:0
	v_fmac_f32_dpp v229, v101, v137 row_shr:15 row_mask:0xf bank_mask:0xf bound_ctrl:0
	v_fmac_f32_dpp v230, v102, v138 row_shr:15 row_mask:0xf bank_mask:0xf bound_ctrl:0
	v_fmac_f32_dpp v231, v103, v139 row_shr:15 row_mask:0xf bank_mask:0xf bound_ctrl:0
	v_fmac_f32_dpp v232, v96, v152 row_shr:15 row_mask:0xf bank_mask:0xf bound_ctrl:0
	v_fmac_f32_dpp v233, v97, v153 row_shr:15 row_mask:0xf bank_mask:0xf bound_ctrl:0
	v_fmac_f32_dpp v234, v98, v154 row_shr:15 row_mask:0xf bank_mask:0xf bound_ctrl:0
	v_fmac_f32_dpp v235, v99, v155 row_shr:15 row_mask:0xf bank_mask:0xf bound_ctrl:0
	v_pk_fma_f32 v[228:229], v[132:133], v[108:109], v[228:229]
	v_pk_fma_f32 v[230:231], v[134:135], v[110:111], v[230:231]
	v_pk_fma_f32 v[232:233], v[148:149], v[104:105], v[232:233]
	v_pk_fma_f32 v[234:235], v[150:151], v[106:107], v[234:235]
	v_fmac_f32_dpp v228, v108, v128 row_shr:1 row_mask:0xf bank_mask:0xf bound_ctrl:0
	v_fmac_f32_dpp v229, v109, v129 row_shr:1 row_mask:0xf bank_mask:0xf bound_ctrl:0
	v_fmac_f32_dpp v230, v110, v130 row_shr:1 row_mask:0xf bank_mask:0xf bound_ctrl:0
	v_fmac_f32_dpp v231, v111, v131 row_shr:1 row_mask:0xf bank_mask:0xf bound_ctrl:0
	v_fmac_f32_dpp v232, v104, v144 row_shr:1 row_mask:0xf bank_mask:0xf bound_ctrl:0
	v_fmac_f32_dpp v233, v105, v145 row_shr:1 row_mask:0xf bank_mask:0xf bound_ctrl:0
	v_fmac_f32_dpp v234, v106, v146 row_shr:1 row_mask:0xf bank_mask:0xf bound_ctrl:0
	v_fmac_f32_dpp v235, v107, v147 row_shr:1 row_mask:0xf bank_mask:0xf bound_ctrl:0
	v_fmac_f32_dpp v228, v116, v128 row_shl:15 row_mask:0xf bank_mask:0xf bound_ctrl:0
	v_fmac_f32_dpp v229, v117, v129 row_shl:15 row_mask:0xf bank_mask:0xf bound_ctrl:0
	v_fmac_f32_dpp v230, v118, v130 row_shl:15 row_mask:0xf bank_mask:0xf bound_ctrl:0
	v_fmac_f32_dpp v231, v119, v131 row_shl:15 row_mask:0xf bank_mask:0xf bound_ctrl:0
	v_fmac_f32_dpp v232, v112, v144 row_shl:15 row_mask:0xf bank_mask:0xf bound_ctrl:0
	v_fmac_f32_dpp v233, v113, v145 row_shl:15 row_mask:0xf bank_mask:0xf bound_ctrl:0
	v_fmac_f32_dpp v234, v114, v146 row_shl:15 row_mask:0xf bank_mask:0xf bound_ctrl:0
	v_fmac_f32_dpp v235, v115, v147 row_shl:15 row_mask:0xf bank_mask:0xf bound_ctrl:0
	v_pk_mul_f32 v[216:217], v[228:229], v[220:221]
	v_pk_mul_f32 v[218:219], v[230:231], v[220:221]
	v_exp_f32_e32 v216, v216
	v_exp_f32_e32 v217, v217
	v_exp_f32_e32 v218, v218
	v_exp_f32_e32 v219, v219
	v_pk_add_f32 v[216:217], v[216:217], v[222:223]
	v_pk_add_f32 v[218:219], v[218:219], v[222:223]
	v_rcp_f32_e32 v216, v216
	v_rcp_f32_e32 v217, v217
	v_rcp_f32_e32 v218, v218
	v_rcp_f32_e32 v219, v219
	v_pk_mul_f32 v[228:229], v[228:229], v[216:217]
	v_pk_mul_f32 v[230:231], v[230:231], v[218:219]
	v_pk_mul_f32 v[228:229], v[232:233], v[228:229]
	v_pk_mul_f32 v[230:231], v[234:235], v[230:231]
	s_add_u32 s8, s90, 0x2c000
	s_addc_u32 s9, s91, 0
	v_cvt_pk_bf16_f32 v224, v228, v229
	v_cvt_pk_bf16_f32 v225, v230, v231
	global_store_dwordx2 v237, v[224:225], s[8:9]
	v_pk_mov_b32 v[228:229], v[140:141], v[140:141] op_sel:[0,1]
	v_pk_mov_b32 v[230:231], v[142:143], v[142:143] op_sel:[0,1]
	v_pk_mov_b32 v[232:233], v[156:157], v[156:157] op_sel:[0,1]
	v_pk_mov_b32 v[234:235], v[158:159], v[158:159] op_sel:[0,1]
	v_fmac_f32_dpp v228, v100, v136 row_shl:1 row_mask:0xf bank_mask:0xf bound_ctrl:0
	v_fmac_f32_dpp v229, v101, v137 row_shl:1 row_mask:0xf bank_mask:0xf bound_ctrl:0
	v_fmac_f32_dpp v230, v102, v138 row_shl:1 row_mask:0xf bank_mask:0xf bound_ctrl:0
	v_fmac_f32_dpp v231, v103, v139 row_shl:1 row_mask:0xf bank_mask:0xf bound_ctrl:0
	v_fmac_f32_dpp v232, v96, v152 row_shl:1 row_mask:0xf bank_mask:0xf bound_ctrl:0
	v_fmac_f32_dpp v233, v97, v153 row_shl:1 row_mask:0xf bank_mask:0xf bound_ctrl:0
	v_fmac_f32_dpp v234, v98, v154 row_shl:1 row_mask:0xf bank_mask:0xf bound_ctrl:0
	v_fmac_f32_dpp v235, v99, v155 row_shl:1 row_mask:0xf bank_mask:0xf bound_ctrl:0
	v_fmac_f32_dpp v228, v180, v136 row_shr:15 row_mask:0xf bank_mask:0xf bound_ctrl:0
	v_fmac_f32_dpp v229, v181, v137 row_shr:15 row_mask:0xf bank_mask:0xf bound_ctrl:0
	v_fmac_f32_dpp v230, v182, v138 row_shr:15 row_mask:0xf bank_mask:0xf bound_ctrl:0
	v_fmac_f32_dpp v231, v183, v139 row_shr:15 row_mask:0xf bank_mask:0xf bound_ctrl:0
	v_fmac_f32_dpp v232, v184, v152 row_shr:15 row_mask:0xf bank_mask:0xf bound_ctrl:0
	v_fmac_f32_dpp v233, v185, v153 row_shr:15 row_mask:0xf bank_mask:0xf bound_ctrl:0
	v_fmac_f32_dpp v234, v186, v154 row_shr:15 row_mask:0xf bank_mask:0xf bound_ctrl:0
	v_fmac_f32_dpp v235, v187, v155 row_shr:15 row_mask:0xf bank_mask:0xf bound_ctrl:0
	ds_read_b128 v[180:183], v226 offset:768
	ds_read_b128 v[184:187], v226 offset:896
	v_pk_fma_f32 v[228:229], v[132:133], v[100:101], v[228:229]
	v_pk_fma_f32 v[230:231], v[134:135], v[102:103], v[230:231]
	v_pk_fma_f32 v[232:233], v[148:149], v[96:97], v[232:233]
	v_pk_fma_f32 v[234:235], v[150:151], v[98:99], v[234:235]
	v_fmac_f32_dpp v228, v100, v128 row_shr:1 row_mask:0xf bank_mask:0xf bound_ctrl:0
	v_fmac_f32_dpp v229, v101, v129 row_shr:1 row_mask:0xf bank_mask:0xf bound_ctrl:0
	v_fmac_f32_dpp v230, v102, v130 row_shr:1 row_mask:0xf bank_mask:0xf bound_ctrl:0
	v_fmac_f32_dpp v231, v103, v131 row_shr:1 row_mask:0xf bank_mask:0xf bound_ctrl:0
	v_fmac_f32_dpp v232, v96, v144 row_shr:1 row_mask:0xf bank_mask:0xf bound_ctrl:0
	v_fmac_f32_dpp v233, v97, v145 row_shr:1 row_mask:0xf bank_mask:0xf bound_ctrl:0
	v_fmac_f32_dpp v234, v98, v146 row_shr:1 row_mask:0xf bank_mask:0xf bound_ctrl:0
	v_fmac_f32_dpp v235, v99, v147 row_shr:1 row_mask:0xf bank_mask:0xf bound_ctrl:0
	v_fmac_f32_dpp v228, v108, v128 row_shl:15 row_mask:0xf bank_mask:0xf bound_ctrl:0
	v_fmac_f32_dpp v229, v109, v129 row_shl:15 row_mask:0xf bank_mask:0xf bound_ctrl:0
	v_fmac_f32_dpp v230, v110, v130 row_shl:15 row_mask:0xf bank_mask:0xf bound_ctrl:0
	v_fmac_f32_dpp v231, v111, v131 row_shl:15 row_mask:0xf bank_mask:0xf bound_ctrl:0
	v_fmac_f32_dpp v232, v104, v144 row_shl:15 row_mask:0xf bank_mask:0xf bound_ctrl:0
	v_fmac_f32_dpp v233, v105, v145 row_shl:15 row_mask:0xf bank_mask:0xf bound_ctrl:0
	v_fmac_f32_dpp v234, v106, v146 row_shl:15 row_mask:0xf bank_mask:0xf bound_ctrl:0
	v_fmac_f32_dpp v235, v107, v147 row_shl:15 row_mask:0xf bank_mask:0xf bound_ctrl:0
	v_pk_mul_f32 v[216:217], v[228:229], v[220:221]
	v_pk_mul_f32 v[218:219], v[230:231], v[220:221]
	v_exp_f32_e32 v216, v216
	v_exp_f32_e32 v217, v217
	v_exp_f32_e32 v218, v218
	v_exp_f32_e32 v219, v219
	v_pk_add_f32 v[216:217], v[216:217], v[222:223]
	v_pk_add_f32 v[218:219], v[218:219], v[222:223]
	v_rcp_f32_e32 v216, v216
	v_rcp_f32_e32 v217, v217
	v_rcp_f32_e32 v218, v218
	v_rcp_f32_e32 v219, v219
	v_pk_mul_f32 v[228:229], v[228:229], v[216:217]
	v_pk_mul_f32 v[230:231], v[230:231], v[218:219]
	v_pk_mul_f32 v[228:229], v[232:233], v[228:229]
	v_pk_mul_f32 v[230:231], v[234:235], v[230:231]
	s_add_u32 s8, s90, 0x42000
	s_addc_u32 s9, s91, 0
	v_cvt_pk_bf16_f32 v224, v228, v229
	v_cvt_pk_bf16_f32 v225, v230, v231
	global_store_dwordx2 v237, v[224:225], s[8:9]
	global_load_dwordx4 v[96:99], v227, s[76:77] offset:16
	global_load_dwordx4 v[112:115], v236, s[76:77] offset:16
	global_load_dwordx4 v[100:103], v227, s[80:81] offset:16
	global_load_dwordx4 v[116:119], v236, s[80:81] offset:16
	global_load_dwordx4 v[104:107], v227, s[86:87] offset:16
	global_load_dwordx4 v[120:123], v236, s[86:87] offset:16
	global_load_dwordx4 v[108:111], v227, s[4:5] offset:16
	global_load_dwordx4 v[124:127], v236, s[4:5] offset:16
	s_waitcnt lgkmcnt(0)
	v_cndmask_b32_e32 v172, 0, v172, vcc
	v_cndmask_b32_e32 v173, 0, v173, vcc
	v_cndmask_b32_e32 v174, 0, v174, vcc
	v_cndmask_b32_e32 v175, 0, v175, vcc
	v_cndmask_b32_e32 v176, 0, v176, vcc
	v_cndmask_b32_e32 v177, 0, v177, vcc
	v_cndmask_b32_e32 v178, 0, v178, vcc
	v_cndmask_b32_e32 v179, 0, v179, vcc
	v_cndmask_b32_e64 v180, 0, v180, s[68:69]
	v_cndmask_b32_e64 v181, 0, v181, s[68:69]
	v_cndmask_b32_e64 v182, 0, v182, s[68:69]
	v_cndmask_b32_e64 v183, 0, v183, s[68:69]
	v_cndmask_b32_e64 v184, 0, v184, s[68:69]
	v_cndmask_b32_e64 v185, 0, v185, s[68:69]
	v_cndmask_b32_e64 v186, 0, v186, s[68:69]
	v_cndmask_b32_e64 v187, 0, v187, s[68:69]
	v_pk_mov_b32 v[228:229], v[140:141], v[140:141] op_sel:[0,1]
	v_pk_mov_b32 v[230:231], v[142:143], v[142:143] op_sel:[0,1]
	v_pk_mov_b32 v[232:233], v[156:157], v[156:157] op_sel:[0,1]
	v_pk_mov_b32 v[234:235], v[158:159], v[158:159] op_sel:[0,1]
	v_fmac_f32_dpp v228, v92, v136 row_shl:1 row_mask:0xf bank_mask:0xf bound_ctrl:0
	v_fmac_f32_dpp v229, v93, v137 row_shl:1 row_mask:0xf bank_mask:0xf bound_ctrl:0
	v_fmac_f32_dpp v230, v94, v138 row_shl:1 row_mask:0xf bank_mask:0xf bound_ctrl:0
	v_fmac_f32_dpp v231, v95, v139 row_shl:1 row_mask:0xf bank_mask:0xf bound_ctrl:0
	v_fmac_f32_dpp v232, v88, v152 row_shl:1 row_mask:0xf bank_mask:0xf bound_ctrl:0
	v_fmac_f32_dpp v233, v89, v153 row_shl:1 row_mask:0xf bank_mask:0xf bound_ctrl:0
	v_fmac_f32_dpp v234, v90, v154 row_shl:1 row_mask:0xf bank_mask:0xf bound_ctrl:0
	v_fmac_f32_dpp v235, v91, v155 row_shl:1 row_mask:0xf bank_mask:0xf bound_ctrl:0
	v_fmac_f32_dpp v228, v84, v136 row_shr:15 row_mask:0xf bank_mask:0xf bound_ctrl:0
	v_fmac_f32_dpp v229, v85, v137 row_shr:15 row_mask:0xf bank_mask:0xf bound_ctrl:0
	v_fmac_f32_dpp v230, v86, v138 row_shr:15 row_mask:0xf bank_mask:0xf bound_ctrl:0
	v_fmac_f32_dpp v231, v87, v139 row_shr:15 row_mask:0xf bank_mask:0xf bound_ctrl:0
	v_fmac_f32_dpp v232, v80, v152 row_shr:15 row_mask:0xf bank_mask:0xf bound_ctrl:0
	v_fmac_f32_dpp v233, v81, v153 row_shr:15 row_mask:0xf bank_mask:0xf bound_ctrl:0
	v_fmac_f32_dpp v234, v82, v154 row_shr:15 row_mask:0xf bank_mask:0xf bound_ctrl:0
	v_fmac_f32_dpp v235, v83, v155 row_shr:15 row_mask:0xf bank_mask:0xf bound_ctrl:0
	v_pk_fma_f32 v[228:229], v[132:133], v[92:93], v[228:229]
	v_pk_fma_f32 v[230:231], v[134:135], v[94:95], v[230:231]
	v_pk_fma_f32 v[232:233], v[148:149], v[88:89], v[232:233]
	v_pk_fma_f32 v[234:235], v[150:151], v[90:91], v[234:235]
	v_fmac_f32_dpp v228, v92, v128 row_shr:1 row_mask:0xf bank_mask:0xf bound_ctrl:0
	v_fmac_f32_dpp v229, v93, v129 row_shr:1 row_mask:0xf bank_mask:0xf bound_ctrl:0
	v_fmac_f32_dpp v230, v94, v130 row_shr:1 row_mask:0xf bank_mask:0xf bound_ctrl:0
	v_fmac_f32_dpp v231, v95, v131 row_shr:1 row_mask:0xf bank_mask:0xf bound_ctrl:0
	v_fmac_f32_dpp v232, v88, v144 row_shr:1 row_mask:0xf bank_mask:0xf bound_ctrl:0
	v_fmac_f32_dpp v233, v89, v145 row_shr:1 row_mask:0xf bank_mask:0xf bound_ctrl:0
	v_fmac_f32_dpp v234, v90, v146 row_shr:1 row_mask:0xf bank_mask:0xf bound_ctrl:0
	v_fmac_f32_dpp v235, v91, v147 row_shr:1 row_mask:0xf bank_mask:0xf bound_ctrl:0
	v_fmac_f32_dpp v228, v172, v128 row_shl:15 row_mask:0xf bank_mask:0xf bound_ctrl:0
	v_fmac_f32_dpp v229, v173, v129 row_shl:15 row_mask:0xf bank_mask:0xf bound_ctrl:0
	v_fmac_f32_dpp v230, v174, v130 row_shl:15 row_mask:0xf bank_mask:0xf bound_ctrl:0
	v_fmac_f32_dpp v231, v175, v131 row_shl:15 row_mask:0xf bank_mask:0xf bound_ctrl:0
	v_fmac_f32_dpp v232, v176, v144 row_shl:15 row_mask:0xf bank_mask:0xf bound_ctrl:0
	v_fmac_f32_dpp v233, v177, v145 row_shl:15 row_mask:0xf bank_mask:0xf bound_ctrl:0
	v_fmac_f32_dpp v234, v178, v146 row_shl:15 row_mask:0xf bank_mask:0xf bound_ctrl:0
	v_fmac_f32_dpp v235, v179, v147 row_shl:15 row_mask:0xf bank_mask:0xf bound_ctrl:0
	v_pk_mul_f32 v[216:217], v[228:229], v[220:221]
	v_pk_mul_f32 v[218:219], v[230:231], v[220:221]
	v_exp_f32_e32 v216, v216
	v_exp_f32_e32 v217, v217
	v_exp_f32_e32 v218, v218
	v_exp_f32_e32 v219, v219
	v_pk_add_f32 v[216:217], v[216:217], v[222:223]
	v_pk_add_f32 v[218:219], v[218:219], v[222:223]
	v_rcp_f32_e32 v216, v216
	v_rcp_f32_e32 v217, v217
	v_rcp_f32_e32 v218, v218
	v_rcp_f32_e32 v219, v219
	v_pk_mul_f32 v[228:229], v[228:229], v[216:217]
	v_pk_mul_f32 v[230:231], v[230:231], v[218:219]
	v_pk_mul_f32 v[228:229], v[232:233], v[228:229]
	v_pk_mul_f32 v[230:231], v[234:235], v[230:231]
	s_add_u32 s8, s90, 0xb0000
	s_addc_u32 s9, s91, 0
	v_cvt_pk_bf16_f32 v224, v228, v229
	v_cvt_pk_bf16_f32 v225, v230, v231
	global_store_dwordx2 v237, v[224:225], s[8:9]
	ds_read_b128 v[172:175], v226 offset:64
	ds_read_b128 v[176:179], v226 offset:192
	v_pk_mov_b32 v[228:229], v[140:141], v[140:141] op_sel:[0,1]
	v_pk_mov_b32 v[230:231], v[142:143], v[142:143] op_sel:[0,1]
	v_pk_mov_b32 v[232:233], v[156:157], v[156:157] op_sel:[0,1]
	v_pk_mov_b32 v[234:235], v[158:159], v[158:159] op_sel:[0,1]
	v_fmac_f32_dpp v228, v84, v136 row_shl:1 row_mask:0xf bank_mask:0xf bound_ctrl:0
	v_fmac_f32_dpp v229, v85, v137 row_shl:1 row_mask:0xf bank_mask:0xf bound_ctrl:0
	v_fmac_f32_dpp v230, v86, v138 row_shl:1 row_mask:0xf bank_mask:0xf bound_ctrl:0
	v_fmac_f32_dpp v231, v87, v139 row_shl:1 row_mask:0xf bank_mask:0xf bound_ctrl:0
	v_fmac_f32_dpp v232, v80, v152 row_shl:1 row_mask:0xf bank_mask:0xf bound_ctrl:0
	v_fmac_f32_dpp v233, v81, v153 row_shl:1 row_mask:0xf bank_mask:0xf bound_ctrl:0
	v_fmac_f32_dpp v234, v82, v154 row_shl:1 row_mask:0xf bank_mask:0xf bound_ctrl:0
	v_fmac_f32_dpp v235, v83, v155 row_shl:1 row_mask:0xf bank_mask:0xf bound_ctrl:0
	v_fmac_f32_dpp v228, v76, v136 row_shr:15 row_mask:0xf bank_mask:0xf bound_ctrl:0
	v_fmac_f32_dpp v229, v77, v137 row_shr:15 row_mask:0xf bank_mask:0xf bound_ctrl:0
	v_fmac_f32_dpp v230, v78, v138 row_shr:15 row_mask:0xf bank_mask:0xf bound_ctrl:0
	v_fmac_f32_dpp v231, v79, v139 row_shr:15 row_mask:0xf bank_mask:0xf bound_ctrl:0
	v_fmac_f32_dpp v232, v68, v152 row_shr:15 row_mask:0xf bank_mask:0xf bound_ctrl:0
	v_fmac_f32_dpp v233, v69, v153 row_shr:15 row_mask:0xf bank_mask:0xf bound_ctrl:0
	v_fmac_f32_dpp v234, v70, v154 row_shr:15 row_mask:0xf bank_mask:0xf bound_ctrl:0
	v_fmac_f32_dpp v235, v71, v155 row_shr:15 row_mask:0xf bank_mask:0xf bound_ctrl:0
	v_pk_fma_f32 v[228:229], v[132:133], v[84:85], v[228:229]
	v_pk_fma_f32 v[230:231], v[134:135], v[86:87], v[230:231]
	v_pk_fma_f32 v[232:233], v[148:149], v[80:81], v[232:233]
	v_pk_fma_f32 v[234:235], v[150:151], v[82:83], v[234:235]
	v_fmac_f32_dpp v228, v84, v128 row_shr:1 row_mask:0xf bank_mask:0xf bound_ctrl:0
	v_fmac_f32_dpp v229, v85, v129 row_shr:1 row_mask:0xf bank_mask:0xf bound_ctrl:0
	v_fmac_f32_dpp v230, v86, v130 row_shr:1 row_mask:0xf bank_mask:0xf bound_ctrl:0
	v_fmac_f32_dpp v231, v87, v131 row_shr:1 row_mask:0xf bank_mask:0xf bound_ctrl:0
	v_fmac_f32_dpp v232, v80, v144 row_shr:1 row_mask:0xf bank_mask:0xf bound_ctrl:0
	v_fmac_f32_dpp v233, v81, v145 row_shr:1 row_mask:0xf bank_mask:0xf bound_ctrl:0
	v_fmac_f32_dpp v234, v82, v146 row_shr:1 row_mask:0xf bank_mask:0xf bound_ctrl:0
	v_fmac_f32_dpp v235, v83, v147 row_shr:1 row_mask:0xf bank_mask:0xf bound_ctrl:0
	v_fmac_f32_dpp v228, v92, v128 row_shl:15 row_mask:0xf bank_mask:0xf bound_ctrl:0
	v_fmac_f32_dpp v229, v93, v129 row_shl:15 row_mask:0xf bank_mask:0xf bound_ctrl:0
	v_fmac_f32_dpp v230, v94, v130 row_shl:15 row_mask:0xf bank_mask:0xf bound_ctrl:0
	v_fmac_f32_dpp v231, v95, v131 row_shl:15 row_mask:0xf bank_mask:0xf bound_ctrl:0
	v_fmac_f32_dpp v232, v88, v144 row_shl:15 row_mask:0xf bank_mask:0xf bound_ctrl:0
	v_fmac_f32_dpp v233, v89, v145 row_shl:15 row_mask:0xf bank_mask:0xf bound_ctrl:0
	v_fmac_f32_dpp v234, v90, v146 row_shl:15 row_mask:0xf bank_mask:0xf bound_ctrl:0
	v_fmac_f32_dpp v235, v91, v147 row_shl:15 row_mask:0xf bank_mask:0xf bound_ctrl:0
	v_pk_mul_f32 v[216:217], v[228:229], v[220:221]
	v_pk_mul_f32 v[218:219], v[230:231], v[220:221]
	v_exp_f32_e32 v216, v216
	v_exp_f32_e32 v217, v217
	v_exp_f32_e32 v218, v218
	v_exp_f32_e32 v219, v219
	v_pk_add_f32 v[216:217], v[216:217], v[222:223]
	v_pk_add_f32 v[218:219], v[218:219], v[222:223]
	v_rcp_f32_e32 v216, v216
	v_rcp_f32_e32 v217, v217
	v_rcp_f32_e32 v218, v218
	v_rcp_f32_e32 v219, v219
	v_pk_mul_f32 v[228:229], v[228:229], v[216:217]
	v_pk_mul_f32 v[230:231], v[230:231], v[218:219]
	v_pk_mul_f32 v[228:229], v[232:233], v[228:229]
	v_pk_mul_f32 v[230:231], v[234:235], v[230:231]
	s_add_u32 s8, s90, 0xc6000
	s_addc_u32 s9, s91, 0
	v_cvt_pk_bf16_f32 v224, v228, v229
	v_cvt_pk_bf16_f32 v225, v230, v231
	global_store_dwordx2 v237, v[224:225], s[8:9]
	v_pk_mov_b32 v[228:229], v[140:141], v[140:141] op_sel:[0,1]
	v_pk_mov_b32 v[230:231], v[142:143], v[142:143] op_sel:[0,1]
	v_pk_mov_b32 v[232:233], v[156:157], v[156:157] op_sel:[0,1]
	v_pk_mov_b32 v[234:235], v[158:159], v[158:159] op_sel:[0,1]
	v_fmac_f32_dpp v228, v76, v136 row_shl:1 row_mask:0xf bank_mask:0xf bound_ctrl:0
	v_fmac_f32_dpp v229, v77, v137 row_shl:1 row_mask:0xf bank_mask:0xf bound_ctrl:0
	v_fmac_f32_dpp v230, v78, v138 row_shl:1 row_mask:0xf bank_mask:0xf bound_ctrl:0
	v_fmac_f32_dpp v231, v79, v139 row_shl:1 row_mask:0xf bank_mask:0xf bound_ctrl:0
	v_fmac_f32_dpp v232, v68, v152 row_shl:1 row_mask:0xf bank_mask:0xf bound_ctrl:0
	v_fmac_f32_dpp v233, v69, v153 row_shl:1 row_mask:0xf bank_mask:0xf bound_ctrl:0
	v_fmac_f32_dpp v234, v70, v154 row_shl:1 row_mask:0xf bank_mask:0xf bound_ctrl:0
	v_fmac_f32_dpp v235, v71, v155 row_shl:1 row_mask:0xf bank_mask:0xf bound_ctrl:0
	v_fmac_f32_dpp v228, v72, v136 row_shr:15 row_mask:0xf bank_mask:0xf bound_ctrl:0
	v_fmac_f32_dpp v229, v73, v137 row_shr:15 row_mask:0xf bank_mask:0xf bound_ctrl:0
	v_fmac_f32_dpp v230, v74, v138 row_shr:15 row_mask:0xf bank_mask:0xf bound_ctrl:0
	v_fmac_f32_dpp v231, v75, v139 row_shr:15 row_mask:0xf bank_mask:0xf bound_ctrl:0
	v_fmac_f32_dpp v232, v64, v152 row_shr:15 row_mask:0xf bank_mask:0xf bound_ctrl:0
	v_fmac_f32_dpp v233, v65, v153 row_shr:15 row_mask:0xf bank_mask:0xf bound_ctrl:0
	v_fmac_f32_dpp v234, v66, v154 row_shr:15 row_mask:0xf bank_mask:0xf bound_ctrl:0
	v_fmac_f32_dpp v235, v67, v155 row_shr:15 row_mask:0xf bank_mask:0xf bound_ctrl:0
	v_pk_fma_f32 v[228:229], v[132:133], v[76:77], v[228:229]
	v_pk_fma_f32 v[230:231], v[134:135], v[78:79], v[230:231]
	v_pk_fma_f32 v[232:233], v[148:149], v[68:69], v[232:233]
	v_pk_fma_f32 v[234:235], v[150:151], v[70:71], v[234:235]
	v_fmac_f32_dpp v228, v76, v128 row_shr:1 row_mask:0xf bank_mask:0xf bound_ctrl:0
	v_fmac_f32_dpp v229, v77, v129 row_shr:1 row_mask:0xf bank_mask:0xf bound_ctrl:0
	v_fmac_f32_dpp v230, v78, v130 row_shr:1 row_mask:0xf bank_mask:0xf bound_ctrl:0
	v_fmac_f32_dpp v231, v79, v131 row_shr:1 row_mask:0xf bank_mask:0xf bound_ctrl:0
	v_fmac_f32_dpp v232, v68, v144 row_shr:1 row_mask:0xf bank_mask:0xf bound_ctrl:0
	v_fmac_f32_dpp v233, v69, v145 row_shr:1 row_mask:0xf bank_mask:0xf bound_ctrl:0
	v_fmac_f32_dpp v234, v70, v146 row_shr:1 row_mask:0xf bank_mask:0xf bound_ctrl:0
	v_fmac_f32_dpp v235, v71, v147 row_shr:1 row_mask:0xf bank_mask:0xf bound_ctrl:0
	v_fmac_f32_dpp v228, v84, v128 row_shl:15 row_mask:0xf bank_mask:0xf bound_ctrl:0
	v_fmac_f32_dpp v229, v85, v129 row_shl:15 row_mask:0xf bank_mask:0xf bound_ctrl:0
	v_fmac_f32_dpp v230, v86, v130 row_shl:15 row_mask:0xf bank_mask:0xf bound_ctrl:0
	v_fmac_f32_dpp v231, v87, v131 row_shl:15 row_mask:0xf bank_mask:0xf bound_ctrl:0
	v_fmac_f32_dpp v232, v80, v144 row_shl:15 row_mask:0xf bank_mask:0xf bound_ctrl:0
	v_fmac_f32_dpp v233, v81, v145 row_shl:15 row_mask:0xf bank_mask:0xf bound_ctrl:0
	v_fmac_f32_dpp v234, v82, v146 row_shl:15 row_mask:0xf bank_mask:0xf bound_ctrl:0
	v_fmac_f32_dpp v235, v83, v147 row_shl:15 row_mask:0xf bank_mask:0xf bound_ctrl:0
	v_pk_mul_f32 v[216:217], v[228:229], v[220:221]
	v_pk_mul_f32 v[218:219], v[230:231], v[220:221]
	v_exp_f32_e32 v216, v216
	v_exp_f32_e32 v217, v217
	v_exp_f32_e32 v218, v218
	v_exp_f32_e32 v219, v219
	v_pk_add_f32 v[216:217], v[216:217], v[222:223]
	v_pk_add_f32 v[218:219], v[218:219], v[222:223]
	v_rcp_f32_e32 v216, v216
	v_rcp_f32_e32 v217, v217
	v_rcp_f32_e32 v218, v218
	v_rcp_f32_e32 v219, v219
	v_pk_mul_f32 v[228:229], v[228:229], v[216:217]
	v_pk_mul_f32 v[230:231], v[230:231], v[218:219]
	v_pk_mul_f32 v[228:229], v[232:233], v[228:229]
	v_pk_mul_f32 v[230:231], v[234:235], v[230:231]
	s_add_u32 s8, s90, 0xdc000
	s_addc_u32 s9, s91, 0
	v_cvt_pk_bf16_f32 v224, v228, v229
	v_cvt_pk_bf16_f32 v225, v230, v231
	global_store_dwordx2 v237, v[224:225], s[8:9]
	v_pk_mov_b32 v[228:229], v[140:141], v[140:141] op_sel:[0,1]
	v_pk_mov_b32 v[230:231], v[142:143], v[142:143] op_sel:[0,1]
	v_pk_mov_b32 v[232:233], v[156:157], v[156:157] op_sel:[0,1]
	v_pk_mov_b32 v[234:235], v[158:159], v[158:159] op_sel:[0,1]
	v_fmac_f32_dpp v228, v72, v136 row_shl:1 row_mask:0xf bank_mask:0xf bound_ctrl:0
	v_fmac_f32_dpp v229, v73, v137 row_shl:1 row_mask:0xf bank_mask:0xf bound_ctrl:0
	v_fmac_f32_dpp v230, v74, v138 row_shl:1 row_mask:0xf bank_mask:0xf bound_ctrl:0
	v_fmac_f32_dpp v231, v75, v139 row_shl:1 row_mask:0xf bank_mask:0xf bound_ctrl:0
	v_fmac_f32_dpp v232, v64, v152 row_shl:1 row_mask:0xf bank_mask:0xf bound_ctrl:0
	v_fmac_f32_dpp v233, v65, v153 row_shl:1 row_mask:0xf bank_mask:0xf bound_ctrl:0
	v_fmac_f32_dpp v234, v66, v154 row_shl:1 row_mask:0xf bank_mask:0xf bound_ctrl:0
	v_fmac_f32_dpp v235, v67, v155 row_shl:1 row_mask:0xf bank_mask:0xf bound_ctrl:0
	v_fmac_f32_dpp v228, v180, v136 row_shr:15 row_mask:0xf bank_mask:0xf bound_ctrl:0
	v_fmac_f32_dpp v229, v181, v137 row_shr:15 row_mask:0xf bank_mask:0xf bound_ctrl:0
	v_fmac_f32_dpp v230, v182, v138 row_shr:15 row_mask:0xf bank_mask:0xf bound_ctrl:0
	v_fmac_f32_dpp v231, v183, v139 row_shr:15 row_mask:0xf bank_mask:0xf bound_ctrl:0
	v_fmac_f32_dpp v232, v184, v152 row_shr:15 row_mask:0xf bank_mask:0xf bound_ctrl:0
	v_fmac_f32_dpp v233, v185, v153 row_shr:15 row_mask:0xf bank_mask:0xf bound_ctrl:0
	v_fmac_f32_dpp v234, v186, v154 row_shr:15 row_mask:0xf bank_mask:0xf bound_ctrl:0
	v_fmac_f32_dpp v235, v187, v155 row_shr:15 row_mask:0xf bank_mask:0xf bound_ctrl:0
	ds_read_b128 v[180:183], v226 offset:320
	ds_read_b128 v[184:187], v226 offset:448
	v_pk_fma_f32 v[228:229], v[132:133], v[72:73], v[228:229]
	v_pk_fma_f32 v[230:231], v[134:135], v[74:75], v[230:231]
	v_pk_fma_f32 v[232:233], v[148:149], v[64:65], v[232:233]
	v_pk_fma_f32 v[234:235], v[150:151], v[66:67], v[234:235]
	v_fmac_f32_dpp v228, v72, v128 row_shr:1 row_mask:0xf bank_mask:0xf bound_ctrl:0
	v_fmac_f32_dpp v229, v73, v129 row_shr:1 row_mask:0xf bank_mask:0xf bound_ctrl:0
	v_fmac_f32_dpp v230, v74, v130 row_shr:1 row_mask:0xf bank_mask:0xf bound_ctrl:0
	v_fmac_f32_dpp v231, v75, v131 row_shr:1 row_mask:0xf bank_mask:0xf bound_ctrl:0
	v_fmac_f32_dpp v232, v64, v144 row_shr:1 row_mask:0xf bank_mask:0xf bound_ctrl:0
	v_fmac_f32_dpp v233, v65, v145 row_shr:1 row_mask:0xf bank_mask:0xf bound_ctrl:0
	v_fmac_f32_dpp v234, v66, v146 row_shr:1 row_mask:0xf bank_mask:0xf bound_ctrl:0
	v_fmac_f32_dpp v235, v67, v147 row_shr:1 row_mask:0xf bank_mask:0xf bound_ctrl:0
	v_fmac_f32_dpp v228, v76, v128 row_shl:15 row_mask:0xf bank_mask:0xf bound_ctrl:0
	v_fmac_f32_dpp v229, v77, v129 row_shl:15 row_mask:0xf bank_mask:0xf bound_ctrl:0
	v_fmac_f32_dpp v230, v78, v130 row_shl:15 row_mask:0xf bank_mask:0xf bound_ctrl:0
	v_fmac_f32_dpp v231, v79, v131 row_shl:15 row_mask:0xf bank_mask:0xf bound_ctrl:0
	v_fmac_f32_dpp v232, v68, v144 row_shl:15 row_mask:0xf bank_mask:0xf bound_ctrl:0
	v_fmac_f32_dpp v233, v69, v145 row_shl:15 row_mask:0xf bank_mask:0xf bound_ctrl:0
	v_fmac_f32_dpp v234, v70, v146 row_shl:15 row_mask:0xf bank_mask:0xf bound_ctrl:0
	v_fmac_f32_dpp v235, v71, v147 row_shl:15 row_mask:0xf bank_mask:0xf bound_ctrl:0
	v_pk_mul_f32 v[216:217], v[228:229], v[220:221]
	v_pk_mul_f32 v[218:219], v[230:231], v[220:221]
	v_exp_f32_e32 v216, v216
	v_exp_f32_e32 v217, v217
	v_exp_f32_e32 v218, v218
	v_exp_f32_e32 v219, v219
	v_pk_add_f32 v[216:217], v[216:217], v[222:223]
	v_pk_add_f32 v[218:219], v[218:219], v[222:223]
	v_rcp_f32_e32 v216, v216
	v_rcp_f32_e32 v217, v217
	v_rcp_f32_e32 v218, v218
	v_rcp_f32_e32 v219, v219
	v_pk_mul_f32 v[228:229], v[228:229], v[216:217]
	v_pk_mul_f32 v[230:231], v[230:231], v[218:219]
	v_pk_mul_f32 v[228:229], v[232:233], v[228:229]
	v_pk_mul_f32 v[230:231], v[234:235], v[230:231]
	s_add_u32 s8, s90, 0xf2000
	s_addc_u32 s9, s91, 0
	v_cvt_pk_bf16_f32 v224, v228, v229
	v_cvt_pk_bf16_f32 v225, v230, v231
	global_store_dwordx2 v237, v[224:225], s[8:9]
	s_waitcnt vmcnt(4) lgkmcnt(0)
	v_cndmask_b32_e64 v172, 0, v172, s[52:53]
	v_cndmask_b32_e64 v173, 0, v173, s[52:53]
	v_cndmask_b32_e64 v174, 0, v174, s[52:53]
	v_cndmask_b32_e64 v175, 0, v175, s[52:53]
	v_cndmask_b32_e64 v176, 0, v176, s[52:53]
	v_cndmask_b32_e64 v177, 0, v177, s[52:53]
	v_cndmask_b32_e64 v178, 0, v178, s[52:53]
	v_cndmask_b32_e64 v179, 0, v179, s[52:53]
	v_cndmask_b32_e32 v180, 0, v180, vcc
	v_cndmask_b32_e32 v181, 0, v181, vcc
	v_cndmask_b32_e32 v182, 0, v182, vcc
	v_cndmask_b32_e32 v183, 0, v183, vcc
	v_cndmask_b32_e32 v184, 0, v184, vcc
	v_cndmask_b32_e32 v185, 0, v185, vcc
	v_cndmask_b32_e32 v186, 0, v186, vcc
	v_cndmask_b32_e32 v187, 0, v187, vcc
	v_pk_mov_b32 v[228:229], v[108:109], v[108:109] op_sel:[0,1]
	v_pk_mov_b32 v[230:231], v[110:111], v[110:111] op_sel:[0,1]
	v_pk_mov_b32 v[232:233], v[124:125], v[124:125] op_sel:[0,1]
	v_pk_mov_b32 v[234:235], v[126:127], v[126:127] op_sel:[0,1]
	v_fmac_f32_dpp v228, v60, v104 row_shl:1 row_mask:0xf bank_mask:0xf bound_ctrl:0
	v_fmac_f32_dpp v229, v61, v105 row_shl:1 row_mask:0xf bank_mask:0xf bound_ctrl:0
	v_fmac_f32_dpp v230, v62, v106 row_shl:1 row_mask:0xf bank_mask:0xf bound_ctrl:0
	v_fmac_f32_dpp v231, v63, v107 row_shl:1 row_mask:0xf bank_mask:0xf bound_ctrl:0
	v_fmac_f32_dpp v232, v56, v120 row_shl:1 row_mask:0xf bank_mask:0xf bound_ctrl:0
	v_fmac_f32_dpp v233, v57, v121 row_shl:1 row_mask:0xf bank_mask:0xf bound_ctrl:0
	v_fmac_f32_dpp v234, v58, v122 row_shl:1 row_mask:0xf bank_mask:0xf bound_ctrl:0
	v_fmac_f32_dpp v235, v59, v123 row_shl:1 row_mask:0xf bank_mask:0xf bound_ctrl:0
	v_fmac_f32_dpp v228, v52, v104 row_shr:15 row_mask:0xf bank_mask:0xf bound_ctrl:0
	v_fmac_f32_dpp v229, v53, v105 row_shr:15 row_mask:0xf bank_mask:0xf bound_ctrl:0
	v_fmac_f32_dpp v230, v54, v106 row_shr:15 row_mask:0xf bank_mask:0xf bound_ctrl:0
	v_fmac_f32_dpp v231, v55, v107 row_shr:15 row_mask:0xf bank_mask:0xf bound_ctrl:0
	v_fmac_f32_dpp v232, v48, v120 row_shr:15 row_mask:0xf bank_mask:0xf bound_ctrl:0
	v_fmac_f32_dpp v233, v49, v121 row_shr:15 row_mask:0xf bank_mask:0xf bound_ctrl:0
	v_fmac_f32_dpp v234, v50, v122 row_shr:15 row_mask:0xf bank_mask:0xf bound_ctrl:0
	v_fmac_f32_dpp v235, v51, v123 row_shr:15 row_mask:0xf bank_mask:0xf bound_ctrl:0
	v_pk_fma_f32 v[228:229], v[100:101], v[60:61], v[228:229]
	v_pk_fma_f32 v[230:231], v[102:103], v[62:63], v[230:231]
	v_pk_fma_f32 v[232:233], v[116:117], v[56:57], v[232:233]
	v_pk_fma_f32 v[234:235], v[118:119], v[58:59], v[234:235]
	v_fmac_f32_dpp v228, v60, v96 row_shr:1 row_mask:0xf bank_mask:0xf bound_ctrl:0
	v_fmac_f32_dpp v229, v61, v97 row_shr:1 row_mask:0xf bank_mask:0xf bound_ctrl:0
	v_fmac_f32_dpp v230, v62, v98 row_shr:1 row_mask:0xf bank_mask:0xf bound_ctrl:0
	v_fmac_f32_dpp v231, v63, v99 row_shr:1 row_mask:0xf bank_mask:0xf bound_ctrl:0
	v_fmac_f32_dpp v232, v56, v112 row_shr:1 row_mask:0xf bank_mask:0xf bound_ctrl:0
	v_fmac_f32_dpp v233, v57, v113 row_shr:1 row_mask:0xf bank_mask:0xf bound_ctrl:0
	v_fmac_f32_dpp v234, v58, v114 row_shr:1 row_mask:0xf bank_mask:0xf bound_ctrl:0
	v_fmac_f32_dpp v235, v59, v115 row_shr:1 row_mask:0xf bank_mask:0xf bound_ctrl:0
	v_fmac_f32_dpp v228, v172, v96 row_shl:15 row_mask:0xf bank_mask:0xf bound_ctrl:0
	v_fmac_f32_dpp v229, v173, v97 row_shl:15 row_mask:0xf bank_mask:0xf bound_ctrl:0
	v_fmac_f32_dpp v230, v174, v98 row_shl:15 row_mask:0xf bank_mask:0xf bound_ctrl:0
	v_fmac_f32_dpp v231, v175, v99 row_shl:15 row_mask:0xf bank_mask:0xf bound_ctrl:0
	v_fmac_f32_dpp v232, v176, v112 row_shl:15 row_mask:0xf bank_mask:0xf bound_ctrl:0
	v_fmac_f32_dpp v233, v177, v113 row_shl:15 row_mask:0xf bank_mask:0xf bound_ctrl:0
	v_fmac_f32_dpp v234, v178, v114 row_shl:15 row_mask:0xf bank_mask:0xf bound_ctrl:0
	v_fmac_f32_dpp v235, v179, v115 row_shl:15 row_mask:0xf bank_mask:0xf bound_ctrl:0
	v_pk_mul_f32 v[216:217], v[228:229], v[220:221]
	v_pk_mul_f32 v[218:219], v[230:231], v[220:221]
	v_exp_f32_e32 v216, v216
	v_exp_f32_e32 v217, v217
	v_exp_f32_e32 v218, v218
	v_exp_f32_e32 v219, v219
	v_pk_add_f32 v[216:217], v[216:217], v[222:223]
	v_pk_add_f32 v[218:219], v[218:219], v[222:223]
	v_rcp_f32_e32 v216, v216
	v_rcp_f32_e32 v217, v217
	v_rcp_f32_e32 v218, v218
	v_rcp_f32_e32 v219, v219
	v_pk_mul_f32 v[228:229], v[228:229], v[216:217]
	v_pk_mul_f32 v[230:231], v[230:231], v[218:219]
	v_pk_mul_f32 v[228:229], v[232:233], v[228:229]
	v_pk_mul_f32 v[230:231], v[234:235], v[230:231]
	s_mov_b64 s[8:9], s[90:91]
	v_cvt_pk_bf16_f32 v224, v228, v229
	v_cvt_pk_bf16_f32 v225, v230, v231
	global_store_dwordx2 v237, v[224:225], s[8:9] offset:8
	ds_read_b128 v[172:175], v226 offset:576
	ds_read_b128 v[176:179], v226 offset:704
	v_pk_mov_b32 v[228:229], v[108:109], v[108:109] op_sel:[0,1]
	v_pk_mov_b32 v[230:231], v[110:111], v[110:111] op_sel:[0,1]
	v_pk_mov_b32 v[232:233], v[124:125], v[124:125] op_sel:[0,1]
	v_pk_mov_b32 v[234:235], v[126:127], v[126:127] op_sel:[0,1]
	v_fmac_f32_dpp v228, v52, v104 row_shl:1 row_mask:0xf bank_mask:0xf bound_ctrl:0
	v_fmac_f32_dpp v229, v53, v105 row_shl:1 row_mask:0xf bank_mask:0xf bound_ctrl:0
	v_fmac_f32_dpp v230, v54, v106 row_shl:1 row_mask:0xf bank_mask:0xf bound_ctrl:0
	v_fmac_f32_dpp v231, v55, v107 row_shl:1 row_mask:0xf bank_mask:0xf bound_ctrl:0
	v_fmac_f32_dpp v232, v48, v120 row_shl:1 row_mask:0xf bank_mask:0xf bound_ctrl:0
	v_fmac_f32_dpp v233, v49, v121 row_shl:1 row_mask:0xf bank_mask:0xf bound_ctrl:0
	v_fmac_f32_dpp v234, v50, v122 row_shl:1 row_mask:0xf bank_mask:0xf bound_ctrl:0
	v_fmac_f32_dpp v235, v51, v123 row_shl:1 row_mask:0xf bank_mask:0xf bound_ctrl:0
	v_fmac_f32_dpp v228, v44, v104 row_shr:15 row_mask:0xf bank_mask:0xf bound_ctrl:0
	v_fmac_f32_dpp v229, v45, v105 row_shr:15 row_mask:0xf bank_mask:0xf bound_ctrl:0
	v_fmac_f32_dpp v230, v46, v106 row_shr:15 row_mask:0xf bank_mask:0xf bound_ctrl:0
	v_fmac_f32_dpp v231, v47, v107 row_shr:15 row_mask:0xf bank_mask:0xf bound_ctrl:0
	v_fmac_f32_dpp v232, v40, v120 row_shr:15 row_mask:0xf bank_mask:0xf bound_ctrl:0
	v_fmac_f32_dpp v233, v41, v121 row_shr:15 row_mask:0xf bank_mask:0xf bound_ctrl:0
	v_fmac_f32_dpp v234, v42, v122 row_shr:15 row_mask:0xf bank_mask:0xf bound_ctrl:0
	v_fmac_f32_dpp v235, v43, v123 row_shr:15 row_mask:0xf bank_mask:0xf bound_ctrl:0
	v_pk_fma_f32 v[228:229], v[100:101], v[52:53], v[228:229]
	v_pk_fma_f32 v[230:231], v[102:103], v[54:55], v[230:231]
	v_pk_fma_f32 v[232:233], v[116:117], v[48:49], v[232:233]
	v_pk_fma_f32 v[234:235], v[118:119], v[50:51], v[234:235]
	v_fmac_f32_dpp v228, v52, v96 row_shr:1 row_mask:0xf bank_mask:0xf bound_ctrl:0
	v_fmac_f32_dpp v229, v53, v97 row_shr:1 row_mask:0xf bank_mask:0xf bound_ctrl:0
	v_fmac_f32_dpp v230, v54, v98 row_shr:1 row_mask:0xf bank_mask:0xf bound_ctrl:0
	v_fmac_f32_dpp v231, v55, v99 row_shr:1 row_mask:0xf bank_mask:0xf bound_ctrl:0
	v_fmac_f32_dpp v232, v48, v112 row_shr:1 row_mask:0xf bank_mask:0xf bound_ctrl:0
	v_fmac_f32_dpp v233, v49, v113 row_shr:1 row_mask:0xf bank_mask:0xf bound_ctrl:0
	v_fmac_f32_dpp v234, v50, v114 row_shr:1 row_mask:0xf bank_mask:0xf bound_ctrl:0
	v_fmac_f32_dpp v235, v51, v115 row_shr:1 row_mask:0xf bank_mask:0xf bound_ctrl:0
	v_fmac_f32_dpp v228, v60, v96 row_shl:15 row_mask:0xf bank_mask:0xf bound_ctrl:0
	v_fmac_f32_dpp v229, v61, v97 row_shl:15 row_mask:0xf bank_mask:0xf bound_ctrl:0
	v_fmac_f32_dpp v230, v62, v98 row_shl:15 row_mask:0xf bank_mask:0xf bound_ctrl:0
	v_fmac_f32_dpp v231, v63, v99 row_shl:15 row_mask:0xf bank_mask:0xf bound_ctrl:0
	v_fmac_f32_dpp v232, v56, v112 row_shl:15 row_mask:0xf bank_mask:0xf bound_ctrl:0
	v_fmac_f32_dpp v233, v57, v113 row_shl:15 row_mask:0xf bank_mask:0xf bound_ctrl:0
	v_fmac_f32_dpp v234, v58, v114 row_shl:15 row_mask:0xf bank_mask:0xf bound_ctrl:0
	v_fmac_f32_dpp v235, v59, v115 row_shl:15 row_mask:0xf bank_mask:0xf bound_ctrl:0
	v_pk_mul_f32 v[216:217], v[228:229], v[220:221]
	v_pk_mul_f32 v[218:219], v[230:231], v[220:221]
	v_exp_f32_e32 v216, v216
	v_exp_f32_e32 v217, v217
	v_exp_f32_e32 v218, v218
	v_exp_f32_e32 v219, v219
	v_pk_add_f32 v[216:217], v[216:217], v[222:223]
	v_pk_add_f32 v[218:219], v[218:219], v[222:223]
	v_rcp_f32_e32 v216, v216
	v_rcp_f32_e32 v217, v217
	v_rcp_f32_e32 v218, v218
	v_rcp_f32_e32 v219, v219
	v_pk_mul_f32 v[228:229], v[228:229], v[216:217]
	v_pk_mul_f32 v[230:231], v[230:231], v[218:219]
	v_pk_mul_f32 v[228:229], v[232:233], v[228:229]
	v_pk_mul_f32 v[230:231], v[234:235], v[230:231]
	s_add_u32 s8, s90, 0x16000
	s_addc_u32 s9, s91, 0
	v_cvt_pk_bf16_f32 v224, v228, v229
	v_cvt_pk_bf16_f32 v225, v230, v231
	global_store_dwordx2 v237, v[224:225], s[8:9] offset:8
	v_pk_mov_b32 v[228:229], v[108:109], v[108:109] op_sel:[0,1]
	v_pk_mov_b32 v[230:231], v[110:111], v[110:111] op_sel:[0,1]
	v_pk_mov_b32 v[232:233], v[124:125], v[124:125] op_sel:[0,1]
	v_pk_mov_b32 v[234:235], v[126:127], v[126:127] op_sel:[0,1]
	v_fmac_f32_dpp v228, v44, v104 row_shl:1 row_mask:0xf bank_mask:0xf bound_ctrl:0
	v_fmac_f32_dpp v229, v45, v105 row_shl:1 row_mask:0xf bank_mask:0xf bound_ctrl:0
	v_fmac_f32_dpp v230, v46, v106 row_shl:1 row_mask:0xf bank_mask:0xf bound_ctrl:0
	v_fmac_f32_dpp v231, v47, v107 row_shl:1 row_mask:0xf bank_mask:0xf bound_ctrl:0
	v_fmac_f32_dpp v232, v40, v120 row_shl:1 row_mask:0xf bank_mask:0xf bound_ctrl:0
	v_fmac_f32_dpp v233, v41, v121 row_shl:1 row_mask:0xf bank_mask:0xf bound_ctrl:0
	v_fmac_f32_dpp v234, v42, v122 row_shl:1 row_mask:0xf bank_mask:0xf bound_ctrl:0
	v_fmac_f32_dpp v235, v43, v123 row_shl:1 row_mask:0xf bank_mask:0xf bound_ctrl:0
	v_fmac_f32_dpp v228, v36, v104 row_shr:15 row_mask:0xf bank_mask:0xf bound_ctrl:0
	v_fmac_f32_dpp v229, v37, v105 row_shr:15 row_mask:0xf bank_mask:0xf bound_ctrl:0
	v_fmac_f32_dpp v230, v38, v106 row_shr:15 row_mask:0xf bank_mask:0xf bound_ctrl:0
	v_fmac_f32_dpp v231, v39, v107 row_shr:15 row_mask:0xf bank_mask:0xf bound_ctrl:0
	v_fmac_f32_dpp v232, v32, v120 row_shr:15 row_mask:0xf bank_mask:0xf bound_ctrl:0
	v_fmac_f32_dpp v233, v33, v121 row_shr:15 row_mask:0xf bank_mask:0xf bound_ctrl:0
	v_fmac_f32_dpp v234, v34, v122 row_shr:15 row_mask:0xf bank_mask:0xf bound_ctrl:0
	v_fmac_f32_dpp v235, v35, v123 row_shr:15 row_mask:0xf bank_mask:0xf bound_ctrl:0
	v_pk_fma_f32 v[228:229], v[100:101], v[44:45], v[228:229]
	v_pk_fma_f32 v[230:231], v[102:103], v[46:47], v[230:231]
	v_pk_fma_f32 v[232:233], v[116:117], v[40:41], v[232:233]
	v_pk_fma_f32 v[234:235], v[118:119], v[42:43], v[234:235]
	v_fmac_f32_dpp v228, v44, v96 row_shr:1 row_mask:0xf bank_mask:0xf bound_ctrl:0
	v_fmac_f32_dpp v229, v45, v97 row_shr:1 row_mask:0xf bank_mask:0xf bound_ctrl:0
	v_fmac_f32_dpp v230, v46, v98 row_shr:1 row_mask:0xf bank_mask:0xf bound_ctrl:0
	v_fmac_f32_dpp v231, v47, v99 row_shr:1 row_mask:0xf bank_mask:0xf bound_ctrl:0
	v_fmac_f32_dpp v232, v40, v112 row_shr:1 row_mask:0xf bank_mask:0xf bound_ctrl:0
	v_fmac_f32_dpp v233, v41, v113 row_shr:1 row_mask:0xf bank_mask:0xf bound_ctrl:0
	v_fmac_f32_dpp v234, v42, v114 row_shr:1 row_mask:0xf bank_mask:0xf bound_ctrl:0
	v_fmac_f32_dpp v235, v43, v115 row_shr:1 row_mask:0xf bank_mask:0xf bound_ctrl:0
	v_fmac_f32_dpp v228, v52, v96 row_shl:15 row_mask:0xf bank_mask:0xf bound_ctrl:0
	v_fmac_f32_dpp v229, v53, v97 row_shl:15 row_mask:0xf bank_mask:0xf bound_ctrl:0
	v_fmac_f32_dpp v230, v54, v98 row_shl:15 row_mask:0xf bank_mask:0xf bound_ctrl:0
	v_fmac_f32_dpp v231, v55, v99 row_shl:15 row_mask:0xf bank_mask:0xf bound_ctrl:0
	v_fmac_f32_dpp v232, v48, v112 row_shl:15 row_mask:0xf bank_mask:0xf bound_ctrl:0
	v_fmac_f32_dpp v233, v49, v113 row_shl:15 row_mask:0xf bank_mask:0xf bound_ctrl:0
	v_fmac_f32_dpp v234, v50, v114 row_shl:15 row_mask:0xf bank_mask:0xf bound_ctrl:0
	v_fmac_f32_dpp v235, v51, v115 row_shl:15 row_mask:0xf bank_mask:0xf bound_ctrl:0
	v_pk_mul_f32 v[216:217], v[228:229], v[220:221]
	v_pk_mul_f32 v[218:219], v[230:231], v[220:221]
	v_exp_f32_e32 v216, v216
	v_exp_f32_e32 v217, v217
	v_exp_f32_e32 v218, v218
	v_exp_f32_e32 v219, v219
	v_pk_add_f32 v[216:217], v[216:217], v[222:223]
	v_pk_add_f32 v[218:219], v[218:219], v[222:223]
	v_rcp_f32_e32 v216, v216
	v_rcp_f32_e32 v217, v217
	v_rcp_f32_e32 v218, v218
	v_rcp_f32_e32 v219, v219
	v_pk_mul_f32 v[228:229], v[228:229], v[216:217]
	v_pk_mul_f32 v[230:231], v[230:231], v[218:219]
	v_pk_mul_f32 v[228:229], v[232:233], v[228:229]
	v_pk_mul_f32 v[230:231], v[234:235], v[230:231]
	s_add_u32 s8, s90, 0x2c000
	s_addc_u32 s9, s91, 0
	v_cvt_pk_bf16_f32 v224, v228, v229
	v_cvt_pk_bf16_f32 v225, v230, v231
	global_store_dwordx2 v237, v[224:225], s[8:9] offset:8
	v_pk_mov_b32 v[228:229], v[108:109], v[108:109] op_sel:[0,1]
	v_pk_mov_b32 v[230:231], v[110:111], v[110:111] op_sel:[0,1]
	v_pk_mov_b32 v[232:233], v[124:125], v[124:125] op_sel:[0,1]
	v_pk_mov_b32 v[234:235], v[126:127], v[126:127] op_sel:[0,1]
	v_fmac_f32_dpp v228, v36, v104 row_shl:1 row_mask:0xf bank_mask:0xf bound_ctrl:0
	v_fmac_f32_dpp v229, v37, v105 row_shl:1 row_mask:0xf bank_mask:0xf bound_ctrl:0
	v_fmac_f32_dpp v230, v38, v106 row_shl:1 row_mask:0xf bank_mask:0xf bound_ctrl:0
	v_fmac_f32_dpp v231, v39, v107 row_shl:1 row_mask:0xf bank_mask:0xf bound_ctrl:0
	v_fmac_f32_dpp v232, v32, v120 row_shl:1 row_mask:0xf bank_mask:0xf bound_ctrl:0
	v_fmac_f32_dpp v233, v33, v121 row_shl:1 row_mask:0xf bank_mask:0xf bound_ctrl:0
	v_fmac_f32_dpp v234, v34, v122 row_shl:1 row_mask:0xf bank_mask:0xf bound_ctrl:0
	v_fmac_f32_dpp v235, v35, v123 row_shl:1 row_mask:0xf bank_mask:0xf bound_ctrl:0
	v_fmac_f32_dpp v228, v180, v104 row_shr:15 row_mask:0xf bank_mask:0xf bound_ctrl:0
	v_fmac_f32_dpp v229, v181, v105 row_shr:15 row_mask:0xf bank_mask:0xf bound_ctrl:0
	v_fmac_f32_dpp v230, v182, v106 row_shr:15 row_mask:0xf bank_mask:0xf bound_ctrl:0
	v_fmac_f32_dpp v231, v183, v107 row_shr:15 row_mask:0xf bank_mask:0xf bound_ctrl:0
	v_fmac_f32_dpp v232, v184, v120 row_shr:15 row_mask:0xf bank_mask:0xf bound_ctrl:0
	v_fmac_f32_dpp v233, v185, v121 row_shr:15 row_mask:0xf bank_mask:0xf bound_ctrl:0
	v_fmac_f32_dpp v234, v186, v122 row_shr:15 row_mask:0xf bank_mask:0xf bound_ctrl:0
	v_fmac_f32_dpp v235, v187, v123 row_shr:15 row_mask:0xf bank_mask:0xf bound_ctrl:0
	ds_read_b128 v[180:183], v226 offset:832
	ds_read_b128 v[184:187], v226 offset:960
	v_pk_fma_f32 v[228:229], v[100:101], v[36:37], v[228:229]
	v_pk_fma_f32 v[230:231], v[102:103], v[38:39], v[230:231]
	v_pk_fma_f32 v[232:233], v[116:117], v[32:33], v[232:233]
	v_pk_fma_f32 v[234:235], v[118:119], v[34:35], v[234:235]
	v_fmac_f32_dpp v228, v36, v96 row_shr:1 row_mask:0xf bank_mask:0xf bound_ctrl:0
	v_fmac_f32_dpp v229, v37, v97 row_shr:1 row_mask:0xf bank_mask:0xf bound_ctrl:0
	v_fmac_f32_dpp v230, v38, v98 row_shr:1 row_mask:0xf bank_mask:0xf bound_ctrl:0
	v_fmac_f32_dpp v231, v39, v99 row_shr:1 row_mask:0xf bank_mask:0xf bound_ctrl:0
	v_fmac_f32_dpp v232, v32, v112 row_shr:1 row_mask:0xf bank_mask:0xf bound_ctrl:0
	v_fmac_f32_dpp v233, v33, v113 row_shr:1 row_mask:0xf bank_mask:0xf bound_ctrl:0
	v_fmac_f32_dpp v234, v34, v114 row_shr:1 row_mask:0xf bank_mask:0xf bound_ctrl:0
	v_fmac_f32_dpp v235, v35, v115 row_shr:1 row_mask:0xf bank_mask:0xf bound_ctrl:0
	v_fmac_f32_dpp v228, v44, v96 row_shl:15 row_mask:0xf bank_mask:0xf bound_ctrl:0
	v_fmac_f32_dpp v229, v45, v97 row_shl:15 row_mask:0xf bank_mask:0xf bound_ctrl:0
	v_fmac_f32_dpp v230, v46, v98 row_shl:15 row_mask:0xf bank_mask:0xf bound_ctrl:0
	v_fmac_f32_dpp v231, v47, v99 row_shl:15 row_mask:0xf bank_mask:0xf bound_ctrl:0
	v_fmac_f32_dpp v232, v40, v112 row_shl:15 row_mask:0xf bank_mask:0xf bound_ctrl:0
	v_fmac_f32_dpp v233, v41, v113 row_shl:15 row_mask:0xf bank_mask:0xf bound_ctrl:0
	v_fmac_f32_dpp v234, v42, v114 row_shl:15 row_mask:0xf bank_mask:0xf bound_ctrl:0
	v_fmac_f32_dpp v235, v43, v115 row_shl:15 row_mask:0xf bank_mask:0xf bound_ctrl:0
	v_pk_mul_f32 v[216:217], v[228:229], v[220:221]
	v_pk_mul_f32 v[218:219], v[230:231], v[220:221]
	v_exp_f32_e32 v216, v216
	v_exp_f32_e32 v217, v217
	v_exp_f32_e32 v218, v218
	v_exp_f32_e32 v219, v219
	v_pk_add_f32 v[216:217], v[216:217], v[222:223]
	v_pk_add_f32 v[218:219], v[218:219], v[222:223]
	v_rcp_f32_e32 v216, v216
	v_rcp_f32_e32 v217, v217
	v_rcp_f32_e32 v218, v218
	v_rcp_f32_e32 v219, v219
	v_pk_mul_f32 v[228:229], v[228:229], v[216:217]
	v_pk_mul_f32 v[230:231], v[230:231], v[218:219]
	v_pk_mul_f32 v[228:229], v[232:233], v[228:229]
	v_pk_mul_f32 v[230:231], v[234:235], v[230:231]
	s_add_u32 s8, s90, 0x42000
	s_addc_u32 s9, s91, 0
	v_cvt_pk_bf16_f32 v224, v228, v229
	v_cvt_pk_bf16_f32 v225, v230, v231
	global_store_dwordx2 v237, v[224:225], s[8:9] offset:8
	s_waitcnt lgkmcnt(0)
	v_cndmask_b32_e32 v172, 0, v172, vcc
	v_cndmask_b32_e32 v173, 0, v173, vcc
	v_cndmask_b32_e32 v174, 0, v174, vcc
	v_cndmask_b32_e32 v175, 0, v175, vcc
	v_cndmask_b32_e32 v176, 0, v176, vcc
	v_cndmask_b32_e32 v177, 0, v177, vcc
	v_cndmask_b32_e32 v178, 0, v178, vcc
	v_cndmask_b32_e32 v179, 0, v179, vcc
	v_cndmask_b32_e64 v180, 0, v180, s[68:69]
	v_cndmask_b32_e64 v181, 0, v181, s[68:69]
	v_cndmask_b32_e64 v182, 0, v182, s[68:69]
	v_cndmask_b32_e64 v183, 0, v183, s[68:69]
	v_cndmask_b32_e64 v184, 0, v184, s[68:69]
	v_cndmask_b32_e64 v185, 0, v185, s[68:69]
	v_cndmask_b32_e64 v186, 0, v186, s[68:69]
	v_cndmask_b32_e64 v187, 0, v187, s[68:69]
	v_pk_mov_b32 v[228:229], v[108:109], v[108:109] op_sel:[0,1]
	v_pk_mov_b32 v[230:231], v[110:111], v[110:111] op_sel:[0,1]
	v_pk_mov_b32 v[232:233], v[124:125], v[124:125] op_sel:[0,1]
	v_pk_mov_b32 v[234:235], v[126:127], v[126:127] op_sel:[0,1]
	v_fmac_f32_dpp v228, v28, v104 row_shl:1 row_mask:0xf bank_mask:0xf bound_ctrl:0
	v_fmac_f32_dpp v229, v29, v105 row_shl:1 row_mask:0xf bank_mask:0xf bound_ctrl:0
	v_fmac_f32_dpp v230, v30, v106 row_shl:1 row_mask:0xf bank_mask:0xf bound_ctrl:0
	v_fmac_f32_dpp v231, v31, v107 row_shl:1 row_mask:0xf bank_mask:0xf bound_ctrl:0
	v_fmac_f32_dpp v232, v24, v120 row_shl:1 row_mask:0xf bank_mask:0xf bound_ctrl:0
	v_fmac_f32_dpp v233, v25, v121 row_shl:1 row_mask:0xf bank_mask:0xf bound_ctrl:0
	v_fmac_f32_dpp v234, v26, v122 row_shl:1 row_mask:0xf bank_mask:0xf bound_ctrl:0
	v_fmac_f32_dpp v235, v27, v123 row_shl:1 row_mask:0xf bank_mask:0xf bound_ctrl:0
	v_fmac_f32_dpp v228, v20, v104 row_shr:15 row_mask:0xf bank_mask:0xf bound_ctrl:0
	v_fmac_f32_dpp v229, v21, v105 row_shr:15 row_mask:0xf bank_mask:0xf bound_ctrl:0
	v_fmac_f32_dpp v230, v22, v106 row_shr:15 row_mask:0xf bank_mask:0xf bound_ctrl:0
	v_fmac_f32_dpp v231, v23, v107 row_shr:15 row_mask:0xf bank_mask:0xf bound_ctrl:0
	v_fmac_f32_dpp v232, v16, v120 row_shr:15 row_mask:0xf bank_mask:0xf bound_ctrl:0
	v_fmac_f32_dpp v233, v17, v121 row_shr:15 row_mask:0xf bank_mask:0xf bound_ctrl:0
	v_fmac_f32_dpp v234, v18, v122 row_shr:15 row_mask:0xf bank_mask:0xf bound_ctrl:0
	v_fmac_f32_dpp v235, v19, v123 row_shr:15 row_mask:0xf bank_mask:0xf bound_ctrl:0
	v_pk_fma_f32 v[228:229], v[100:101], v[28:29], v[228:229]
	v_pk_fma_f32 v[230:231], v[102:103], v[30:31], v[230:231]
	v_pk_fma_f32 v[232:233], v[116:117], v[24:25], v[232:233]
	v_pk_fma_f32 v[234:235], v[118:119], v[26:27], v[234:235]
	v_fmac_f32_dpp v228, v28, v96 row_shr:1 row_mask:0xf bank_mask:0xf bound_ctrl:0
	v_fmac_f32_dpp v229, v29, v97 row_shr:1 row_mask:0xf bank_mask:0xf bound_ctrl:0
	v_fmac_f32_dpp v230, v30, v98 row_shr:1 row_mask:0xf bank_mask:0xf bound_ctrl:0
	v_fmac_f32_dpp v231, v31, v99 row_shr:1 row_mask:0xf bank_mask:0xf bound_ctrl:0
	v_fmac_f32_dpp v232, v24, v112 row_shr:1 row_mask:0xf bank_mask:0xf bound_ctrl:0
	v_fmac_f32_dpp v233, v25, v113 row_shr:1 row_mask:0xf bank_mask:0xf bound_ctrl:0
	v_fmac_f32_dpp v234, v26, v114 row_shr:1 row_mask:0xf bank_mask:0xf bound_ctrl:0
	v_fmac_f32_dpp v235, v27, v115 row_shr:1 row_mask:0xf bank_mask:0xf bound_ctrl:0
	v_fmac_f32_dpp v228, v172, v96 row_shl:15 row_mask:0xf bank_mask:0xf bound_ctrl:0
	v_fmac_f32_dpp v229, v173, v97 row_shl:15 row_mask:0xf bank_mask:0xf bound_ctrl:0
	v_fmac_f32_dpp v230, v174, v98 row_shl:15 row_mask:0xf bank_mask:0xf bound_ctrl:0
	v_fmac_f32_dpp v231, v175, v99 row_shl:15 row_mask:0xf bank_mask:0xf bound_ctrl:0
	v_fmac_f32_dpp v232, v176, v112 row_shl:15 row_mask:0xf bank_mask:0xf bound_ctrl:0
	v_fmac_f32_dpp v233, v177, v113 row_shl:15 row_mask:0xf bank_mask:0xf bound_ctrl:0
	v_fmac_f32_dpp v234, v178, v114 row_shl:15 row_mask:0xf bank_mask:0xf bound_ctrl:0
	v_fmac_f32_dpp v235, v179, v115 row_shl:15 row_mask:0xf bank_mask:0xf bound_ctrl:0
	v_pk_mul_f32 v[216:217], v[228:229], v[220:221]
	v_pk_mul_f32 v[218:219], v[230:231], v[220:221]
	v_exp_f32_e32 v216, v216
	v_exp_f32_e32 v217, v217
	v_exp_f32_e32 v218, v218
	v_exp_f32_e32 v219, v219
	v_pk_add_f32 v[216:217], v[216:217], v[222:223]
	v_pk_add_f32 v[218:219], v[218:219], v[222:223]
	v_rcp_f32_e32 v216, v216
	v_rcp_f32_e32 v217, v217
	v_rcp_f32_e32 v218, v218
	v_rcp_f32_e32 v219, v219
	v_pk_mul_f32 v[228:229], v[228:229], v[216:217]
	v_pk_mul_f32 v[230:231], v[230:231], v[218:219]
	v_pk_mul_f32 v[228:229], v[232:233], v[228:229]
	v_pk_mul_f32 v[230:231], v[234:235], v[230:231]
	s_add_u32 s8, s90, 0xb0000
	s_addc_u32 s9, s91, 0
	v_cvt_pk_bf16_f32 v224, v228, v229
	v_cvt_pk_bf16_f32 v225, v230, v231
	global_store_dwordx2 v237, v[224:225], s[8:9] offset:8
	v_pk_mov_b32 v[228:229], v[108:109], v[108:109] op_sel:[0,1]
	v_pk_mov_b32 v[230:231], v[110:111], v[110:111] op_sel:[0,1]
	v_pk_mov_b32 v[232:233], v[124:125], v[124:125] op_sel:[0,1]
	v_pk_mov_b32 v[234:235], v[126:127], v[126:127] op_sel:[0,1]
	v_fmac_f32_dpp v228, v20, v104 row_shl:1 row_mask:0xf bank_mask:0xf bound_ctrl:0
	v_fmac_f32_dpp v229, v21, v105 row_shl:1 row_mask:0xf bank_mask:0xf bound_ctrl:0
	v_fmac_f32_dpp v230, v22, v106 row_shl:1 row_mask:0xf bank_mask:0xf bound_ctrl:0
	v_fmac_f32_dpp v231, v23, v107 row_shl:1 row_mask:0xf bank_mask:0xf bound_ctrl:0
	v_fmac_f32_dpp v232, v16, v120 row_shl:1 row_mask:0xf bank_mask:0xf bound_ctrl:0
	v_fmac_f32_dpp v233, v17, v121 row_shl:1 row_mask:0xf bank_mask:0xf bound_ctrl:0
	v_fmac_f32_dpp v234, v18, v122 row_shl:1 row_mask:0xf bank_mask:0xf bound_ctrl:0
	v_fmac_f32_dpp v235, v19, v123 row_shl:1 row_mask:0xf bank_mask:0xf bound_ctrl:0
	v_fmac_f32_dpp v228, v12, v104 row_shr:15 row_mask:0xf bank_mask:0xf bound_ctrl:0
	v_fmac_f32_dpp v229, v13, v105 row_shr:15 row_mask:0xf bank_mask:0xf bound_ctrl:0
	v_fmac_f32_dpp v230, v14, v106 row_shr:15 row_mask:0xf bank_mask:0xf bound_ctrl:0
	v_fmac_f32_dpp v231, v15, v107 row_shr:15 row_mask:0xf bank_mask:0xf bound_ctrl:0
	v_fmac_f32_dpp v232, v8, v120 row_shr:15 row_mask:0xf bank_mask:0xf bound_ctrl:0
	v_fmac_f32_dpp v233, v9, v121 row_shr:15 row_mask:0xf bank_mask:0xf bound_ctrl:0
	v_fmac_f32_dpp v234, v10, v122 row_shr:15 row_mask:0xf bank_mask:0xf bound_ctrl:0
	v_fmac_f32_dpp v235, v11, v123 row_shr:15 row_mask:0xf bank_mask:0xf bound_ctrl:0
	v_pk_fma_f32 v[228:229], v[100:101], v[20:21], v[228:229]
	v_pk_fma_f32 v[230:231], v[102:103], v[22:23], v[230:231]
	v_pk_fma_f32 v[232:233], v[116:117], v[16:17], v[232:233]
	v_pk_fma_f32 v[234:235], v[118:119], v[18:19], v[234:235]
	v_fmac_f32_dpp v228, v20, v96 row_shr:1 row_mask:0xf bank_mask:0xf bound_ctrl:0
	v_fmac_f32_dpp v229, v21, v97 row_shr:1 row_mask:0xf bank_mask:0xf bound_ctrl:0
	v_fmac_f32_dpp v230, v22, v98 row_shr:1 row_mask:0xf bank_mask:0xf bound_ctrl:0
	v_fmac_f32_dpp v231, v23, v99 row_shr:1 row_mask:0xf bank_mask:0xf bound_ctrl:0
	v_fmac_f32_dpp v232, v16, v112 row_shr:1 row_mask:0xf bank_mask:0xf bound_ctrl:0
	v_fmac_f32_dpp v233, v17, v113 row_shr:1 row_mask:0xf bank_mask:0xf bound_ctrl:0
	v_fmac_f32_dpp v234, v18, v114 row_shr:1 row_mask:0xf bank_mask:0xf bound_ctrl:0
	v_fmac_f32_dpp v235, v19, v115 row_shr:1 row_mask:0xf bank_mask:0xf bound_ctrl:0
	v_fmac_f32_dpp v228, v28, v96 row_shl:15 row_mask:0xf bank_mask:0xf bound_ctrl:0
	v_fmac_f32_dpp v229, v29, v97 row_shl:15 row_mask:0xf bank_mask:0xf bound_ctrl:0
	v_fmac_f32_dpp v230, v30, v98 row_shl:15 row_mask:0xf bank_mask:0xf bound_ctrl:0
	v_fmac_f32_dpp v231, v31, v99 row_shl:15 row_mask:0xf bank_mask:0xf bound_ctrl:0
	v_fmac_f32_dpp v232, v24, v112 row_shl:15 row_mask:0xf bank_mask:0xf bound_ctrl:0
	v_fmac_f32_dpp v233, v25, v113 row_shl:15 row_mask:0xf bank_mask:0xf bound_ctrl:0
	v_fmac_f32_dpp v234, v26, v114 row_shl:15 row_mask:0xf bank_mask:0xf bound_ctrl:0
	v_fmac_f32_dpp v235, v27, v115 row_shl:15 row_mask:0xf bank_mask:0xf bound_ctrl:0
	v_pk_mul_f32 v[216:217], v[228:229], v[220:221]
	v_pk_mul_f32 v[218:219], v[230:231], v[220:221]
	v_exp_f32_e32 v216, v216
	v_exp_f32_e32 v217, v217
	v_exp_f32_e32 v218, v218
	v_exp_f32_e32 v219, v219
	v_pk_add_f32 v[216:217], v[216:217], v[222:223]
	v_pk_add_f32 v[218:219], v[218:219], v[222:223]
	v_rcp_f32_e32 v216, v216
	v_rcp_f32_e32 v217, v217
	v_rcp_f32_e32 v218, v218
	v_rcp_f32_e32 v219, v219
	v_pk_mul_f32 v[228:229], v[228:229], v[216:217]
	v_pk_mul_f32 v[230:231], v[230:231], v[218:219]
	v_pk_mul_f32 v[228:229], v[232:233], v[228:229]
	v_pk_mul_f32 v[230:231], v[234:235], v[230:231]
	s_add_u32 s8, s90, 0xc6000
	s_addc_u32 s9, s91, 0
	v_cvt_pk_bf16_f32 v224, v228, v229
	v_cvt_pk_bf16_f32 v225, v230, v231
	global_store_dwordx2 v237, v[224:225], s[8:9] offset:8
	v_pk_mov_b32 v[228:229], v[108:109], v[108:109] op_sel:[0,1]
	v_pk_mov_b32 v[230:231], v[110:111], v[110:111] op_sel:[0,1]
	v_pk_mov_b32 v[232:233], v[124:125], v[124:125] op_sel:[0,1]
	v_pk_mov_b32 v[234:235], v[126:127], v[126:127] op_sel:[0,1]
	v_fmac_f32_dpp v228, v12, v104 row_shl:1 row_mask:0xf bank_mask:0xf bound_ctrl:0
	v_fmac_f32_dpp v229, v13, v105 row_shl:1 row_mask:0xf bank_mask:0xf bound_ctrl:0
	v_fmac_f32_dpp v230, v14, v106 row_shl:1 row_mask:0xf bank_mask:0xf bound_ctrl:0
	v_fmac_f32_dpp v231, v15, v107 row_shl:1 row_mask:0xf bank_mask:0xf bound_ctrl:0
	v_fmac_f32_dpp v232, v8, v120 row_shl:1 row_mask:0xf bank_mask:0xf bound_ctrl:0
	v_fmac_f32_dpp v233, v9, v121 row_shl:1 row_mask:0xf bank_mask:0xf bound_ctrl:0
	v_fmac_f32_dpp v234, v10, v122 row_shl:1 row_mask:0xf bank_mask:0xf bound_ctrl:0
	v_fmac_f32_dpp v235, v11, v123 row_shl:1 row_mask:0xf bank_mask:0xf bound_ctrl:0
	v_fmac_f32_dpp v228, v4, v104 row_shr:15 row_mask:0xf bank_mask:0xf bound_ctrl:0
	v_fmac_f32_dpp v229, v5, v105 row_shr:15 row_mask:0xf bank_mask:0xf bound_ctrl:0
	v_fmac_f32_dpp v230, v6, v106 row_shr:15 row_mask:0xf bank_mask:0xf bound_ctrl:0
	v_fmac_f32_dpp v231, v7, v107 row_shr:15 row_mask:0xf bank_mask:0xf bound_ctrl:0
	v_fmac_f32_dpp v232, v0, v120 row_shr:15 row_mask:0xf bank_mask:0xf bound_ctrl:0
	v_fmac_f32_dpp v233, v1, v121 row_shr:15 row_mask:0xf bank_mask:0xf bound_ctrl:0
	v_fmac_f32_dpp v234, v2, v122 row_shr:15 row_mask:0xf bank_mask:0xf bound_ctrl:0
	v_fmac_f32_dpp v235, v3, v123 row_shr:15 row_mask:0xf bank_mask:0xf bound_ctrl:0
	v_pk_fma_f32 v[228:229], v[100:101], v[12:13], v[228:229]
	v_pk_fma_f32 v[230:231], v[102:103], v[14:15], v[230:231]
	v_pk_fma_f32 v[232:233], v[116:117], v[8:9], v[232:233]
	v_pk_fma_f32 v[234:235], v[118:119], v[10:11], v[234:235]
	v_fmac_f32_dpp v228, v12, v96 row_shr:1 row_mask:0xf bank_mask:0xf bound_ctrl:0
	v_fmac_f32_dpp v229, v13, v97 row_shr:1 row_mask:0xf bank_mask:0xf bound_ctrl:0
	v_fmac_f32_dpp v230, v14, v98 row_shr:1 row_mask:0xf bank_mask:0xf bound_ctrl:0
	v_fmac_f32_dpp v231, v15, v99 row_shr:1 row_mask:0xf bank_mask:0xf bound_ctrl:0
	v_fmac_f32_dpp v232, v8, v112 row_shr:1 row_mask:0xf bank_mask:0xf bound_ctrl:0
	v_fmac_f32_dpp v233, v9, v113 row_shr:1 row_mask:0xf bank_mask:0xf bound_ctrl:0
	v_fmac_f32_dpp v234, v10, v114 row_shr:1 row_mask:0xf bank_mask:0xf bound_ctrl:0
	v_fmac_f32_dpp v235, v11, v115 row_shr:1 row_mask:0xf bank_mask:0xf bound_ctrl:0
	v_fmac_f32_dpp v228, v20, v96 row_shl:15 row_mask:0xf bank_mask:0xf bound_ctrl:0
	v_fmac_f32_dpp v229, v21, v97 row_shl:15 row_mask:0xf bank_mask:0xf bound_ctrl:0
	v_fmac_f32_dpp v230, v22, v98 row_shl:15 row_mask:0xf bank_mask:0xf bound_ctrl:0
	v_fmac_f32_dpp v231, v23, v99 row_shl:15 row_mask:0xf bank_mask:0xf bound_ctrl:0
	v_fmac_f32_dpp v232, v16, v112 row_shl:15 row_mask:0xf bank_mask:0xf bound_ctrl:0
	v_fmac_f32_dpp v233, v17, v113 row_shl:15 row_mask:0xf bank_mask:0xf bound_ctrl:0
	v_fmac_f32_dpp v234, v18, v114 row_shl:15 row_mask:0xf bank_mask:0xf bound_ctrl:0
	v_fmac_f32_dpp v235, v19, v115 row_shl:15 row_mask:0xf bank_mask:0xf bound_ctrl:0
	v_pk_mul_f32 v[216:217], v[228:229], v[220:221]
	v_pk_mul_f32 v[218:219], v[230:231], v[220:221]
	v_exp_f32_e32 v216, v216
	v_exp_f32_e32 v217, v217
	v_exp_f32_e32 v218, v218
	v_exp_f32_e32 v219, v219
	v_pk_add_f32 v[216:217], v[216:217], v[222:223]
	v_pk_add_f32 v[218:219], v[218:219], v[222:223]
	v_rcp_f32_e32 v216, v216
	v_rcp_f32_e32 v217, v217
	v_rcp_f32_e32 v218, v218
	v_rcp_f32_e32 v219, v219
	v_pk_mul_f32 v[228:229], v[228:229], v[216:217]
	v_pk_mul_f32 v[230:231], v[230:231], v[218:219]
	v_pk_mul_f32 v[228:229], v[232:233], v[228:229]
	v_pk_mul_f32 v[230:231], v[234:235], v[230:231]
	s_add_u32 s8, s90, 0xdc000
	s_addc_u32 s9, s91, 0
	v_cvt_pk_bf16_f32 v224, v228, v229
	v_cvt_pk_bf16_f32 v225, v230, v231
	global_store_dwordx2 v237, v[224:225], s[8:9] offset:8
	v_pk_mov_b32 v[228:229], v[108:109], v[108:109] op_sel:[0,1]
	v_pk_mov_b32 v[230:231], v[110:111], v[110:111] op_sel:[0,1]
	v_pk_mov_b32 v[232:233], v[124:125], v[124:125] op_sel:[0,1]
	v_pk_mov_b32 v[234:235], v[126:127], v[126:127] op_sel:[0,1]
	v_fmac_f32_dpp v228, v4, v104 row_shl:1 row_mask:0xf bank_mask:0xf bound_ctrl:0
	v_fmac_f32_dpp v229, v5, v105 row_shl:1 row_mask:0xf bank_mask:0xf bound_ctrl:0
	v_fmac_f32_dpp v230, v6, v106 row_shl:1 row_mask:0xf bank_mask:0xf bound_ctrl:0
	v_fmac_f32_dpp v231, v7, v107 row_shl:1 row_mask:0xf bank_mask:0xf bound_ctrl:0
	v_fmac_f32_dpp v232, v0, v120 row_shl:1 row_mask:0xf bank_mask:0xf bound_ctrl:0
	v_fmac_f32_dpp v233, v1, v121 row_shl:1 row_mask:0xf bank_mask:0xf bound_ctrl:0
	v_fmac_f32_dpp v234, v2, v122 row_shl:1 row_mask:0xf bank_mask:0xf bound_ctrl:0
	v_fmac_f32_dpp v235, v3, v123 row_shl:1 row_mask:0xf bank_mask:0xf bound_ctrl:0
	v_fmac_f32_dpp v228, v180, v104 row_shr:15 row_mask:0xf bank_mask:0xf bound_ctrl:0
	v_fmac_f32_dpp v229, v181, v105 row_shr:15 row_mask:0xf bank_mask:0xf bound_ctrl:0
	v_fmac_f32_dpp v230, v182, v106 row_shr:15 row_mask:0xf bank_mask:0xf bound_ctrl:0
	v_fmac_f32_dpp v231, v183, v107 row_shr:15 row_mask:0xf bank_mask:0xf bound_ctrl:0
	v_fmac_f32_dpp v232, v184, v120 row_shr:15 row_mask:0xf bank_mask:0xf bound_ctrl:0
	v_fmac_f32_dpp v233, v185, v121 row_shr:15 row_mask:0xf bank_mask:0xf bound_ctrl:0
	v_fmac_f32_dpp v234, v186, v122 row_shr:15 row_mask:0xf bank_mask:0xf bound_ctrl:0
	v_fmac_f32_dpp v235, v187, v123 row_shr:15 row_mask:0xf bank_mask:0xf bound_ctrl:0
	v_pk_fma_f32 v[228:229], v[100:101], v[4:5], v[228:229]
	v_pk_fma_f32 v[230:231], v[102:103], v[6:7], v[230:231]
	v_pk_fma_f32 v[232:233], v[116:117], v[0:1], v[232:233]
	v_pk_fma_f32 v[234:235], v[118:119], v[2:3], v[234:235]
	v_fmac_f32_dpp v228, v4, v96 row_shr:1 row_mask:0xf bank_mask:0xf bound_ctrl:0
	v_fmac_f32_dpp v229, v5, v97 row_shr:1 row_mask:0xf bank_mask:0xf bound_ctrl:0
	v_fmac_f32_dpp v230, v6, v98 row_shr:1 row_mask:0xf bank_mask:0xf bound_ctrl:0
	v_fmac_f32_dpp v231, v7, v99 row_shr:1 row_mask:0xf bank_mask:0xf bound_ctrl:0
	v_fmac_f32_dpp v232, v0, v112 row_shr:1 row_mask:0xf bank_mask:0xf bound_ctrl:0
	v_fmac_f32_dpp v233, v1, v113 row_shr:1 row_mask:0xf bank_mask:0xf bound_ctrl:0
	v_fmac_f32_dpp v234, v2, v114 row_shr:1 row_mask:0xf bank_mask:0xf bound_ctrl:0
	v_fmac_f32_dpp v235, v3, v115 row_shr:1 row_mask:0xf bank_mask:0xf bound_ctrl:0
	v_fmac_f32_dpp v228, v12, v96 row_shl:15 row_mask:0xf bank_mask:0xf bound_ctrl:0
	v_fmac_f32_dpp v229, v13, v97 row_shl:15 row_mask:0xf bank_mask:0xf bound_ctrl:0
	v_fmac_f32_dpp v230, v14, v98 row_shl:15 row_mask:0xf bank_mask:0xf bound_ctrl:0
	v_fmac_f32_dpp v231, v15, v99 row_shl:15 row_mask:0xf bank_mask:0xf bound_ctrl:0
	v_fmac_f32_dpp v232, v8, v112 row_shl:15 row_mask:0xf bank_mask:0xf bound_ctrl:0
	v_fmac_f32_dpp v233, v9, v113 row_shl:15 row_mask:0xf bank_mask:0xf bound_ctrl:0
	v_fmac_f32_dpp v234, v10, v114 row_shl:15 row_mask:0xf bank_mask:0xf bound_ctrl:0
	v_fmac_f32_dpp v235, v11, v115 row_shl:15 row_mask:0xf bank_mask:0xf bound_ctrl:0
	v_pk_mul_f32 v[216:217], v[228:229], v[220:221]
	v_pk_mul_f32 v[218:219], v[230:231], v[220:221]
	v_exp_f32_e32 v216, v216
	v_exp_f32_e32 v217, v217
	v_exp_f32_e32 v218, v218
	v_exp_f32_e32 v219, v219
	v_pk_add_f32 v[216:217], v[216:217], v[222:223]
	v_pk_add_f32 v[218:219], v[218:219], v[222:223]
	v_rcp_f32_e32 v216, v216
	v_rcp_f32_e32 v217, v217
	v_rcp_f32_e32 v218, v218
	v_rcp_f32_e32 v219, v219
	v_pk_mul_f32 v[228:229], v[228:229], v[216:217]
	v_pk_mul_f32 v[230:231], v[230:231], v[218:219]
	v_pk_mul_f32 v[228:229], v[232:233], v[228:229]
	v_pk_mul_f32 v[230:231], v[234:235], v[230:231]
	s_add_u32 s8, s90, 0xf2000
	s_addc_u32 s9, s91, 0
	v_cvt_pk_bf16_f32 v224, v228, v229
	v_cvt_pk_bf16_f32 v225, v230, v231
	global_store_dwordx2 v237, v[224:225], s[8:9] offset:8
	s_andn2_b64 vcc, exec, s[82:83]
	s_mov_b64 s[4:5], -1
	s_cbranch_vccnz .LBB0_43
	s_andn2_b64 vcc, exec, s[88:89]
	s_cbranch_vccnz .LBB0_42
	s_barrier
	s_branch .LBB0_42
